# agent-scope (sc1) stores in the epilogues of the two-unit GEMM phases (ffn_out, a_out, b_in, b_out)
# speedup vs baseline: 1.0073x; 1.0073x over previous
.LBB0_162:
	s_lshl_b32 s17, s17, 8
	v_lshl_or_b32 v172, s16, 8, v187
	v_add_u32_e32 v176, s17, v185
	v_ashrrev_i32_e32 v173, 31, v172
	v_lshlrev_b64 v[202:203], 1, v[172:173]
	v_ashrrev_i32_e32 v177, 31, v176
	v_lshl_add_u64 v[174:175], s[22:23], 0, v[202:203]
	v_lshlrev_b64 v[204:205], 11, v[176:177]
	v_lshl_add_u64 v[128:129], v[174:175], 0, v[204:205]
	global_load_dwordx4 v[194:197], v[128:129], off
	global_load_dwordx4 v[198:201], v[128:129], off offset:256
	v_or_b32_e32 v128, 16, v176
	v_or_b32_e32 v130, 32, v176
	v_or_b32_e32 v132, 48, v176
	v_ashrrev_i32_e32 v129, 31, v128
	v_ashrrev_i32_e32 v131, 31, v130
	v_ashrrev_i32_e32 v133, 31, v132
	v_lshlrev_b64 v[182:183], 11, v[128:129]
	v_lshlrev_b64 v[180:181], 11, v[130:131]
	v_lshlrev_b64 v[178:179], 11, v[132:133]
	v_lshl_add_u64 v[128:129], v[174:175], 0, v[182:183]
	v_lshl_add_u64 v[130:131], v[174:175], 0, v[180:181]
	v_lshl_add_u64 v[206:207], v[174:175], 0, v[178:179]
	global_load_dwordx4 v[148:151], v[128:129], off
	global_load_dwordx4 v[144:147], v[128:129], off offset:256
	global_load_dwordx4 v[140:143], v[130:131], off
	global_load_dwordx4 v[136:139], v[130:131], off offset:256
	global_load_dwordx4 v[132:135], v[206:207], off
	s_nop 0
	global_load_dwordx4 v[128:131], v[206:207], off offset:256
	v_and_b32_e32 v206, 64, v159
	v_xor_b32_e32 v193, 16, v159
	v_add_u32_e32 v206, 64, v206
	v_xor_b32_e32 v207, 32, v159
	v_cmp_lt_i32_e32 vcc, v193, v206
	v_lshl_add_u64 v[204:205], s[22:23], 0, v[204:205]
	v_lshl_add_u64 v[202:203], v[204:205], 0, v[202:203]
	v_cndmask_b32_e32 v193, v159, v193, vcc
	v_cmp_lt_i32_e32 vcc, v207, v206
	v_lshlrev_b32_e32 v193, 2, v193
	s_waitcnt vmcnt(0)
	v_lshlrev_b32_e32 v204, 16, v194
	v_and_b32_e32 v205, 0xffff0000, v194
	v_lshlrev_b32_e32 v194, 16, v195
	v_and_b32_e32 v195, 0xffff0000, v195
	v_cndmask_b32_e32 v212, v159, v207, vcc
	v_lshlrev_b32_e32 v206, 16, v196
	v_and_b32_e32 v207, 0xffff0000, v196
	v_lshlrev_b32_e32 v196, 16, v197
	v_and_b32_e32 v197, 0xffff0000, v197
	v_lshlrev_b32_e32 v210, 16, v200
	v_and_b32_e32 v211, 0xffff0000, v200
	v_lshlrev_b32_e32 v200, 16, v201
	v_and_b32_e32 v201, 0xffff0000, v201
	v_pk_fma_f32 v[126:127], v[126:127], 0.5, v[194:195] op_sel_hi:[1,0,1]
	v_pk_fma_f32 v[124:125], v[124:125], 0.5, v[204:205] op_sel_hi:[1,0,1]
	v_pk_fma_f32 v[122:123], v[122:123], 0.5, v[196:197] op_sel_hi:[1,0,1]
	v_pk_fma_f32 v[196:197], v[114:115], 0.5, v[200:201] op_sel_hi:[1,0,1]
	v_pk_mul_f32 v[114:115], v[126:127], v[126:127]
	v_pk_fma_f32 v[120:121], v[120:121], 0.5, v[206:207] op_sel_hi:[1,0,1]
	v_pk_fma_f32 v[114:115], v[124:125], v[124:125], v[114:115]
	v_lshlrev_b32_e32 v208, 16, v198
	v_and_b32_e32 v209, 0xffff0000, v198
	v_pk_fma_f32 v[114:115], v[120:121], v[120:121], v[114:115]
	v_lshlrev_b32_e32 v198, 16, v199
	v_and_b32_e32 v199, 0xffff0000, v199
	v_pk_fma_f32 v[116:117], v[116:117], 0.5, v[208:209] op_sel_hi:[1,0,1]
	v_pk_fma_f32 v[114:115], v[122:123], v[122:123], v[114:115]
	v_pk_fma_f32 v[118:119], v[118:119], 0.5, v[198:199] op_sel_hi:[1,0,1]
	v_pk_fma_f32 v[114:115], v[116:117], v[116:117], v[114:115]
	v_pk_fma_f32 v[194:195], v[112:113], 0.5, v[210:211] op_sel_hi:[1,0,1]
	v_pk_fma_f32 v[114:115], v[118:119], v[118:119], v[114:115]
	v_cvt_pk_bf16_f32 v112, v124, v125
	v_cvt_pk_bf16_f32 v113, v126, v127
	s_nop 0
	v_pk_fma_f32 v[114:115], v[194:195], v[194:195], v[114:115]
	s_nop 0
	v_pk_fma_f32 v[114:115], v[196:197], v[196:197], v[114:115]
	s_nop 0
	v_add_f32_e32 v124, v114, v115
	ds_bpermute_b32 v125, v193, v124
	v_cvt_pk_bf16_f32 v114, v120, v121
	v_cvt_pk_bf16_f32 v115, v122, v123
	global_store_dwordx4 v[202:203], v[112:115], off sc1
	v_cvt_pk_bf16_f32 v116, v116, v117
	v_cvt_pk_bf16_f32 v117, v118, v119
	v_cvt_pk_bf16_f32 v118, v194, v195
	v_cvt_pk_bf16_f32 v119, v196, v197
	global_store_dwordx4 v[202:203], v[116:119], off offset:256 sc1
	s_waitcnt lgkmcnt(0)
	v_add_f32_e32 v113, v124, v125
	v_lshlrev_b32_e32 v112, 2, v212
	ds_bpermute_b32 v114, v112, v113
	s_and_saveexec_b64 s[54:55], s[8:9]
	s_cbranch_execz .LBB0_164
	s_waitcnt lgkmcnt(0)
	v_add_f32_e32 v113, v113, v114
	ds_write_b32 v188, v113
.LBB0_164:
	s_or_b64 exec, exec, s[54:55]
	v_lshlrev_b32_e32 v116, 16, v149
	v_and_b32_e32 v117, 0xffff0000, v149
	s_waitcnt lgkmcnt(0)
	v_lshlrev_b32_e32 v114, 16, v148
	v_and_b32_e32 v115, 0xffff0000, v148
	v_pk_fma_f32 v[110:111], v[110:111], 0.5, v[116:117] op_sel_hi:[1,0,1]
	v_pk_fma_f32 v[114:115], v[108:109], 0.5, v[114:115] op_sel_hi:[1,0,1]
	v_pk_mul_f32 v[116:117], v[110:111], v[110:111]
	v_cvt_pk_bf16_f32 v108, v114, v115
	v_cvt_pk_bf16_f32 v109, v110, v111
	v_lshlrev_b32_e32 v110, 16, v150
	v_and_b32_e32 v111, 0xffff0000, v150
	v_pk_fma_f32 v[114:115], v[114:115], v[114:115], v[116:117]
	v_pk_fma_f32 v[104:105], v[104:105], 0.5, v[110:111] op_sel_hi:[1,0,1]
	s_nop 0
	v_pk_fma_f32 v[114:115], v[104:105], v[104:105], v[114:115]
	v_cvt_pk_bf16_f32 v110, v104, v105
	v_lshlrev_b32_e32 v104, 16, v151
	v_and_b32_e32 v105, 0xffff0000, v151
	v_pk_fma_f32 v[104:105], v[106:107], 0.5, v[104:105] op_sel_hi:[1,0,1]
	s_nop 0
	v_pk_fma_f32 v[106:107], v[104:105], v[104:105], v[114:115]
	v_cvt_pk_bf16_f32 v111, v104, v105
	v_lshlrev_b32_e32 v104, 16, v144
	v_and_b32_e32 v105, 0xffff0000, v144
	v_pk_fma_f32 v[100:101], v[100:101], 0.5, v[104:105] op_sel_hi:[1,0,1]
	s_nop 0
	v_pk_fma_f32 v[104:105], v[100:101], v[100:101], v[106:107]
	v_lshlrev_b32_e32 v106, 16, v145
	v_and_b32_e32 v107, 0xffff0000, v145
	v_pk_fma_f32 v[102:103], v[102:103], 0.5, v[106:107] op_sel_hi:[1,0,1]
	v_lshlrev_b32_e32 v106, 16, v146
	v_and_b32_e32 v107, 0xffff0000, v146
	v_pk_fma_f32 v[104:105], v[102:103], v[102:103], v[104:105]
	v_pk_fma_f32 v[106:107], v[96:97], 0.5, v[106:107] op_sel_hi:[1,0,1]
	s_nop 0
	v_pk_fma_f32 v[96:97], v[106:107], v[106:107], v[104:105]
	v_lshlrev_b32_e32 v104, 16, v147
	v_and_b32_e32 v105, 0xffff0000, v147
	v_pk_fma_f32 v[104:105], v[98:99], 0.5, v[104:105] op_sel_hi:[1,0,1]
	s_nop 0
	v_pk_fma_f32 v[96:97], v[104:105], v[104:105], v[96:97]
	s_nop 0
	v_add_f32_e32 v99, v96, v97
	ds_bpermute_b32 v113, v193, v99
	v_lshl_add_u64 v[96:97], s[22:23], 0, v[182:183]
	v_lshl_add_u64 v[114:115], v[172:173], 1, v[96:97]
	global_store_dwordx4 v[114:115], v[108:111], off sc1
	v_cvt_pk_bf16_f32 v98, v100, v101
	s_waitcnt lgkmcnt(0)
	v_add_f32_e32 v96, v99, v113
	ds_bpermute_b32 v97, v112, v96
	v_cvt_pk_bf16_f32 v99, v102, v103
	v_cvt_pk_bf16_f32 v100, v106, v107
	v_cvt_pk_bf16_f32 v101, v104, v105
	global_store_dwordx4 v[114:115], v[98:101], off offset:256 sc1
	s_and_saveexec_b64 s[54:55], s[8:9]
	s_cbranch_execz .LBB0_166
	s_waitcnt lgkmcnt(0)
	v_add_f32_e32 v96, v96, v97
	ds_write_b32 v188, v96 offset:256
.LBB0_166:
	s_or_b64 exec, exec, s[54:55]
	v_lshlrev_b32_e32 v98, 16, v141
	v_and_b32_e32 v99, 0xffff0000, v141
	v_lshlrev_b32_e32 v96, 16, v140
	s_waitcnt lgkmcnt(0)
	v_and_b32_e32 v97, 0xffff0000, v140
	v_pk_fma_f32 v[94:95], v[94:95], 0.5, v[98:99] op_sel_hi:[1,0,1]
	v_pk_fma_f32 v[96:97], v[92:93], 0.5, v[96:97] op_sel_hi:[1,0,1]
	v_pk_mul_f32 v[98:99], v[94:95], v[94:95]
	v_cvt_pk_bf16_f32 v92, v96, v97
	v_cvt_pk_bf16_f32 v93, v94, v95
	v_lshlrev_b32_e32 v94, 16, v142
	v_and_b32_e32 v95, 0xffff0000, v142
	v_pk_fma_f32 v[96:97], v[96:97], v[96:97], v[98:99]
	v_pk_fma_f32 v[88:89], v[88:89], 0.5, v[94:95] op_sel_hi:[1,0,1]
	s_nop 0
	v_pk_fma_f32 v[96:97], v[88:89], v[88:89], v[96:97]
	v_cvt_pk_bf16_f32 v94, v88, v89
	v_lshlrev_b32_e32 v88, 16, v143
	v_and_b32_e32 v89, 0xffff0000, v143
	v_pk_fma_f32 v[88:89], v[90:91], 0.5, v[88:89] op_sel_hi:[1,0,1]
	s_nop 0
	v_pk_fma_f32 v[90:91], v[88:89], v[88:89], v[96:97]
	v_cvt_pk_bf16_f32 v95, v88, v89
	v_lshlrev_b32_e32 v88, 16, v136
	v_and_b32_e32 v89, 0xffff0000, v136
	v_pk_fma_f32 v[84:85], v[84:85], 0.5, v[88:89] op_sel_hi:[1,0,1]
	s_nop 0
	v_pk_fma_f32 v[88:89], v[84:85], v[84:85], v[90:91]
	v_lshlrev_b32_e32 v90, 16, v137
	v_and_b32_e32 v91, 0xffff0000, v137
	v_pk_fma_f32 v[86:87], v[86:87], 0.5, v[90:91] op_sel_hi:[1,0,1]
	v_lshlrev_b32_e32 v90, 16, v138
	v_and_b32_e32 v91, 0xffff0000, v138
	v_pk_fma_f32 v[88:89], v[86:87], v[86:87], v[88:89]
	v_pk_fma_f32 v[90:91], v[80:81], 0.5, v[90:91] op_sel_hi:[1,0,1]
	s_nop 0
	v_pk_fma_f32 v[80:81], v[90:91], v[90:91], v[88:89]
	v_lshlrev_b32_e32 v88, 16, v139
	v_and_b32_e32 v89, 0xffff0000, v139
	v_pk_fma_f32 v[88:89], v[82:83], 0.5, v[88:89] op_sel_hi:[1,0,1]
	s_nop 0
	v_pk_fma_f32 v[80:81], v[88:89], v[88:89], v[80:81]
	s_nop 0
	v_add_f32_e32 v83, v80, v81
	ds_bpermute_b32 v98, v193, v83
	v_lshl_add_u64 v[80:81], s[22:23], 0, v[180:181]
	v_lshl_add_u64 v[96:97], v[172:173], 1, v[80:81]
	global_store_dwordx4 v[96:97], v[92:95], off sc1
	v_cvt_pk_bf16_f32 v82, v84, v85
	s_waitcnt lgkmcnt(0)
	v_add_f32_e32 v80, v83, v98
	ds_bpermute_b32 v81, v112, v80
	v_cvt_pk_bf16_f32 v83, v86, v87
	v_cvt_pk_bf16_f32 v84, v90, v91
	v_cvt_pk_bf16_f32 v85, v88, v89
	global_store_dwordx4 v[96:97], v[82:85], off offset:256 sc1
	s_and_saveexec_b64 s[54:55], s[8:9]
	s_cbranch_execz .LBB0_168
	s_waitcnt lgkmcnt(0)
	v_add_f32_e32 v80, v80, v81
	ds_write_b32 v188, v80 offset:512
.LBB0_168:
	s_or_b64 exec, exec, s[54:55]
	v_lshlrev_b32_e32 v82, 16, v133
	v_and_b32_e32 v83, 0xffff0000, v133
	v_lshlrev_b32_e32 v80, 16, v132
	s_waitcnt lgkmcnt(0)
	v_and_b32_e32 v81, 0xffff0000, v132
	v_pk_fma_f32 v[78:79], v[78:79], 0.5, v[82:83] op_sel_hi:[1,0,1]
	v_pk_fma_f32 v[80:81], v[76:77], 0.5, v[80:81] op_sel_hi:[1,0,1]
	v_pk_mul_f32 v[82:83], v[78:79], v[78:79]
	v_cvt_pk_bf16_f32 v76, v80, v81
	v_cvt_pk_bf16_f32 v77, v78, v79
	v_lshlrev_b32_e32 v78, 16, v134
	v_and_b32_e32 v79, 0xffff0000, v134
	v_pk_fma_f32 v[80:81], v[80:81], v[80:81], v[82:83]
	v_pk_fma_f32 v[72:73], v[72:73], 0.5, v[78:79] op_sel_hi:[1,0,1]
	s_nop 0
	v_pk_fma_f32 v[80:81], v[72:73], v[72:73], v[80:81]
	v_cvt_pk_bf16_f32 v78, v72, v73
	v_lshlrev_b32_e32 v72, 16, v135
	v_and_b32_e32 v73, 0xffff0000, v135
	v_pk_fma_f32 v[72:73], v[74:75], 0.5, v[72:73] op_sel_hi:[1,0,1]
	s_nop 0
	v_pk_fma_f32 v[74:75], v[72:73], v[72:73], v[80:81]
	v_cvt_pk_bf16_f32 v79, v72, v73
	v_lshlrev_b32_e32 v72, 16, v128
	v_and_b32_e32 v73, 0xffff0000, v128
	v_pk_fma_f32 v[68:69], v[68:69], 0.5, v[72:73] op_sel_hi:[1,0,1]
	s_nop 0
	v_pk_fma_f32 v[72:73], v[68:69], v[68:69], v[74:75]
	v_lshlrev_b32_e32 v74, 16, v129
	v_and_b32_e32 v75, 0xffff0000, v129
	v_pk_fma_f32 v[70:71], v[70:71], 0.5, v[74:75] op_sel_hi:[1,0,1]
	v_lshlrev_b32_e32 v74, 16, v130
	v_and_b32_e32 v75, 0xffff0000, v130
	v_pk_fma_f32 v[72:73], v[70:71], v[70:71], v[72:73]
	v_pk_fma_f32 v[74:75], v[64:65], 0.5, v[74:75] op_sel_hi:[1,0,1]
	s_nop 0
	v_pk_fma_f32 v[64:65], v[74:75], v[74:75], v[72:73]
	v_lshlrev_b32_e32 v72, 16, v131
	v_and_b32_e32 v73, 0xffff0000, v131
	v_pk_fma_f32 v[72:73], v[66:67], 0.5, v[72:73] op_sel_hi:[1,0,1]
	s_nop 0
	v_pk_fma_f32 v[64:65], v[72:73], v[72:73], v[64:65]
	s_nop 0
	v_add_f32_e32 v67, v64, v65
	ds_bpermute_b32 v82, v193, v67
	v_lshl_add_u64 v[64:65], s[22:23], 0, v[178:179]
	v_lshl_add_u64 v[80:81], v[172:173], 1, v[64:65]
	global_store_dwordx4 v[80:81], v[76:79], off sc1
	v_cvt_pk_bf16_f32 v66, v68, v69
	s_waitcnt lgkmcnt(0)
	v_add_f32_e32 v64, v67, v82
	ds_bpermute_b32 v65, v112, v64
	v_cvt_pk_bf16_f32 v67, v70, v71
	v_cvt_pk_bf16_f32 v68, v74, v75
	v_cvt_pk_bf16_f32 v69, v72, v73
	global_store_dwordx4 v[80:81], v[66:69], off offset:256 sc1
	s_and_saveexec_b64 s[54:55], s[8:9]
	s_cbranch_execz .LBB0_170
	s_waitcnt lgkmcnt(0)
	v_add_f32_e32 v64, v64, v65
	ds_write_b32 v188, v64 offset:768
.LBB0_170:
	s_or_b64 exec, exec, s[54:55]
	s_waitcnt lgkmcnt(0)
	v_lshlrev_b64 v[64:65], 11, v[176:177]
	v_lshl_add_u64 v[102:103], v[64:65], 0, s[44:45]
	v_lshl_add_u64 v[66:67], v[174:175], 0, v[102:103]
	global_load_dwordx4 v[94:97], v[66:67], off
	global_load_dwordx4 v[98:101], v[66:67], off offset:256
	v_lshl_add_u64 v[92:93], v[64:65], 0, s[46:47]
	v_lshl_add_u64 v[90:91], v[64:65], 0, s[48:49]
	v_lshl_add_u64 v[88:89], v[64:65], 0, s[50:51]
	v_lshl_add_u64 v[64:65], v[174:175], 0, v[92:93]
	v_lshl_add_u64 v[66:67], v[174:175], 0, v[90:91]
	v_lshl_add_u64 v[104:105], v[174:175], 0, v[88:89]
	global_load_dwordx4 v[84:87], v[64:65], off
	global_load_dwordx4 v[80:83], v[64:65], off offset:256
	global_load_dwordx4 v[76:79], v[66:67], off
	global_load_dwordx4 v[72:75], v[66:67], off offset:256
	global_load_dwordx4 v[68:71], v[104:105], off
	s_nop 0
	global_load_dwordx4 v[64:67], v[104:105], off offset:256
	s_waitcnt vmcnt(7)
	v_lshlrev_b32_e32 v104, 16, v94
	v_and_b32_e32 v105, 0xffff0000, v94
	v_lshlrev_b32_e32 v94, 16, v95
	v_and_b32_e32 v95, 0xffff0000, v95
	v_lshlrev_b32_e32 v106, 16, v96
	v_and_b32_e32 v107, 0xffff0000, v96
	v_lshlrev_b32_e32 v96, 16, v97
	v_and_b32_e32 v97, 0xffff0000, v97
	s_waitcnt vmcnt(6)
	v_lshlrev_b32_e32 v108, 16, v98
	v_and_b32_e32 v109, 0xffff0000, v98
	v_lshlrev_b32_e32 v98, 16, v99
	v_and_b32_e32 v99, 0xffff0000, v99
	v_lshlrev_b32_e32 v110, 16, v100
	v_and_b32_e32 v111, 0xffff0000, v100
	v_pk_fma_f32 v[62:63], v[62:63], 0.5, v[94:95] op_sel_hi:[1,0,1]
	v_pk_fma_f32 v[60:61], v[60:61], 0.5, v[104:105] op_sel_hi:[1,0,1]
	v_pk_fma_f32 v[58:59], v[58:59], 0.5, v[96:97] op_sel_hi:[1,0,1]
	v_pk_fma_f32 v[96:97], v[54:55], 0.5, v[98:99] op_sel_hi:[1,0,1]
	v_pk_fma_f32 v[98:99], v[48:49], 0.5, v[110:111] op_sel_hi:[1,0,1]
	v_pk_mul_f32 v[48:49], v[62:63], v[62:63]
	v_pk_fma_f32 v[56:57], v[56:57], 0.5, v[106:107] op_sel_hi:[1,0,1]
	v_pk_fma_f32 v[48:49], v[60:61], v[60:61], v[48:49]
	v_pk_fma_f32 v[94:95], v[52:53], 0.5, v[108:109] op_sel_hi:[1,0,1]
	v_pk_fma_f32 v[48:49], v[56:57], v[56:57], v[48:49]
	v_lshlrev_b32_e32 v100, 16, v101
	v_pk_fma_f32 v[48:49], v[58:59], v[58:59], v[48:49]
	v_and_b32_e32 v101, 0xffff0000, v101
	v_pk_fma_f32 v[48:49], v[94:95], v[94:95], v[48:49]
	v_cvt_pk_bf16_f32 v52, v60, v61
	v_cvt_pk_bf16_f32 v53, v62, v63
	v_cvt_pk_bf16_f32 v54, v56, v57
	v_pk_fma_f32 v[56:57], v[50:51], 0.5, v[100:101] op_sel_hi:[1,0,1]
	v_pk_fma_f32 v[48:49], v[96:97], v[96:97], v[48:49]
	v_cvt_pk_bf16_f32 v55, v58, v59
	s_nop 0
	v_pk_fma_f32 v[48:49], v[98:99], v[98:99], v[48:49]
	s_nop 0
	v_pk_fma_f32 v[48:49], v[56:57], v[56:57], v[48:49]
	s_nop 0
	v_add_f32_e32 v51, v48, v49
	ds_bpermute_b32 v60, v193, v51
	v_lshl_add_u64 v[48:49], s[22:23], 0, v[102:103]
	v_lshl_add_u64 v[58:59], v[172:173], 1, v[48:49]
	global_store_dwordx4 v[58:59], v[52:55], off sc1
	v_cvt_pk_bf16_f32 v50, v94, v95
	s_waitcnt lgkmcnt(0)
	v_add_f32_e32 v48, v51, v60
	ds_bpermute_b32 v49, v112, v48
	v_cvt_pk_bf16_f32 v51, v96, v97
	v_cvt_pk_bf16_f32 v52, v98, v99
	v_cvt_pk_bf16_f32 v53, v56, v57
	global_store_dwordx4 v[58:59], v[50:53], off offset:256 sc1
	s_and_saveexec_b64 s[54:55], s[8:9]
	s_cbranch_execz .LBB0_172
	s_waitcnt lgkmcnt(0)
	v_add_f32_e32 v48, v48, v49
	ds_write_b32 v188, v48 offset:2048
.LBB0_172:
	s_or_b64 exec, exec, s[54:55]
	s_waitcnt vmcnt(7)
	v_lshlrev_b32_e32 v50, 16, v85
	v_and_b32_e32 v51, 0xffff0000, v85
	v_lshlrev_b32_e32 v48, 16, v84
	s_waitcnt lgkmcnt(0)
	v_and_b32_e32 v49, 0xffff0000, v84
	v_pk_fma_f32 v[46:47], v[46:47], 0.5, v[50:51] op_sel_hi:[1,0,1]
	v_pk_fma_f32 v[48:49], v[44:45], 0.5, v[48:49] op_sel_hi:[1,0,1]
	v_pk_mul_f32 v[50:51], v[46:47], v[46:47]
	v_cvt_pk_bf16_f32 v44, v48, v49
	v_cvt_pk_bf16_f32 v45, v46, v47
	v_lshlrev_b32_e32 v46, 16, v86
	v_and_b32_e32 v47, 0xffff0000, v86
	v_pk_fma_f32 v[48:49], v[48:49], v[48:49], v[50:51]
	v_pk_fma_f32 v[40:41], v[40:41], 0.5, v[46:47] op_sel_hi:[1,0,1]
	s_nop 0
	v_pk_fma_f32 v[48:49], v[40:41], v[40:41], v[48:49]
	v_cvt_pk_bf16_f32 v46, v40, v41
	v_lshlrev_b32_e32 v40, 16, v87
	v_and_b32_e32 v41, 0xffff0000, v87
	v_pk_fma_f32 v[40:41], v[42:43], 0.5, v[40:41] op_sel_hi:[1,0,1]
	s_nop 0
	v_pk_fma_f32 v[42:43], v[40:41], v[40:41], v[48:49]
	v_cvt_pk_bf16_f32 v47, v40, v41
	s_waitcnt vmcnt(6)
	v_lshlrev_b32_e32 v40, 16, v80
	v_and_b32_e32 v41, 0xffff0000, v80
	v_pk_fma_f32 v[36:37], v[36:37], 0.5, v[40:41] op_sel_hi:[1,0,1]
	s_nop 0
	v_pk_fma_f32 v[40:41], v[36:37], v[36:37], v[42:43]
	v_lshlrev_b32_e32 v42, 16, v81
	v_and_b32_e32 v43, 0xffff0000, v81
	v_pk_fma_f32 v[38:39], v[38:39], 0.5, v[42:43] op_sel_hi:[1,0,1]
	v_lshlrev_b32_e32 v42, 16, v82
	v_and_b32_e32 v43, 0xffff0000, v82
	v_pk_fma_f32 v[40:41], v[38:39], v[38:39], v[40:41]
	v_pk_fma_f32 v[42:43], v[32:33], 0.5, v[42:43] op_sel_hi:[1,0,1]
	s_nop 0
	v_pk_fma_f32 v[32:33], v[42:43], v[42:43], v[40:41]
	v_lshlrev_b32_e32 v40, 16, v83
	v_and_b32_e32 v41, 0xffff0000, v83
	v_pk_fma_f32 v[40:41], v[34:35], 0.5, v[40:41] op_sel_hi:[1,0,1]
	s_nop 0
	v_pk_fma_f32 v[32:33], v[40:41], v[40:41], v[32:33]
	s_nop 0
	v_add_f32_e32 v35, v32, v33
	ds_bpermute_b32 v50, v193, v35
	v_lshl_add_u64 v[32:33], s[22:23], 0, v[92:93]
	v_lshl_add_u64 v[48:49], v[172:173], 1, v[32:33]
	global_store_dwordx4 v[48:49], v[44:47], off sc1
	v_cvt_pk_bf16_f32 v34, v36, v37
	s_waitcnt lgkmcnt(0)
	v_add_f32_e32 v32, v35, v50
	ds_bpermute_b32 v33, v112, v32
	v_cvt_pk_bf16_f32 v35, v38, v39
	v_cvt_pk_bf16_f32 v36, v42, v43
	v_cvt_pk_bf16_f32 v37, v40, v41
	global_store_dwordx4 v[48:49], v[34:37], off offset:256 sc1
	s_and_saveexec_b64 s[54:55], s[8:9]
	s_cbranch_execz .LBB0_174
	s_waitcnt lgkmcnt(0)
	v_add_f32_e32 v32, v32, v33
	ds_write_b32 v188, v32 offset:2304
.LBB0_174:
	s_or_b64 exec, exec, s[54:55]
	s_waitcnt vmcnt(7)
	v_lshlrev_b32_e32 v34, 16, v77
	v_and_b32_e32 v35, 0xffff0000, v77
	v_lshlrev_b32_e32 v32, 16, v76
	s_waitcnt lgkmcnt(0)
	v_and_b32_e32 v33, 0xffff0000, v76
	v_pk_fma_f32 v[30:31], v[30:31], 0.5, v[34:35] op_sel_hi:[1,0,1]
	v_pk_fma_f32 v[32:33], v[28:29], 0.5, v[32:33] op_sel_hi:[1,0,1]
	v_pk_mul_f32 v[34:35], v[30:31], v[30:31]
	v_cvt_pk_bf16_f32 v28, v32, v33
	v_cvt_pk_bf16_f32 v29, v30, v31
	v_lshlrev_b32_e32 v30, 16, v78
	v_and_b32_e32 v31, 0xffff0000, v78
	v_pk_fma_f32 v[32:33], v[32:33], v[32:33], v[34:35]
	v_pk_fma_f32 v[24:25], v[24:25], 0.5, v[30:31] op_sel_hi:[1,0,1]
	s_nop 0
	v_pk_fma_f32 v[32:33], v[24:25], v[24:25], v[32:33]
	v_cvt_pk_bf16_f32 v30, v24, v25
	v_lshlrev_b32_e32 v24, 16, v79
	v_and_b32_e32 v25, 0xffff0000, v79
	v_pk_fma_f32 v[24:25], v[26:27], 0.5, v[24:25] op_sel_hi:[1,0,1]
	s_nop 0
	v_pk_fma_f32 v[26:27], v[24:25], v[24:25], v[32:33]
	v_cvt_pk_bf16_f32 v31, v24, v25
	s_waitcnt vmcnt(6)
	v_lshlrev_b32_e32 v24, 16, v72
	v_and_b32_e32 v25, 0xffff0000, v72
	v_pk_fma_f32 v[20:21], v[20:21], 0.5, v[24:25] op_sel_hi:[1,0,1]
	s_nop 0
	v_pk_fma_f32 v[24:25], v[20:21], v[20:21], v[26:27]
	v_lshlrev_b32_e32 v26, 16, v73
	v_and_b32_e32 v27, 0xffff0000, v73
	v_pk_fma_f32 v[22:23], v[22:23], 0.5, v[26:27] op_sel_hi:[1,0,1]
	v_lshlrev_b32_e32 v26, 16, v74
	v_and_b32_e32 v27, 0xffff0000, v74
	v_pk_fma_f32 v[24:25], v[22:23], v[22:23], v[24:25]
	v_pk_fma_f32 v[26:27], v[16:17], 0.5, v[26:27] op_sel_hi:[1,0,1]
	s_nop 0
	v_pk_fma_f32 v[16:17], v[26:27], v[26:27], v[24:25]
	v_lshlrev_b32_e32 v24, 16, v75
	v_and_b32_e32 v25, 0xffff0000, v75
	v_pk_fma_f32 v[24:25], v[18:19], 0.5, v[24:25] op_sel_hi:[1,0,1]
	s_nop 0
	v_pk_fma_f32 v[16:17], v[24:25], v[24:25], v[16:17]
	s_nop 0
	v_add_f32_e32 v19, v16, v17
	ds_bpermute_b32 v34, v193, v19
	v_lshl_add_u64 v[16:17], s[22:23], 0, v[90:91]
	v_lshl_add_u64 v[32:33], v[172:173], 1, v[16:17]
	global_store_dwordx4 v[32:33], v[28:31], off sc1
	v_cvt_pk_bf16_f32 v18, v20, v21
	s_waitcnt lgkmcnt(0)
	v_add_f32_e32 v16, v19, v34
	ds_bpermute_b32 v17, v112, v16
	v_cvt_pk_bf16_f32 v19, v22, v23
	v_cvt_pk_bf16_f32 v20, v26, v27
	v_cvt_pk_bf16_f32 v21, v24, v25
	global_store_dwordx4 v[32:33], v[18:21], off offset:256 sc1
	s_and_saveexec_b64 s[54:55], s[8:9]
	s_cbranch_execz .LBB0_176
	s_waitcnt lgkmcnt(0)
	v_add_f32_e32 v16, v16, v17
	ds_write_b32 v188, v16 offset:2560
.LBB0_176:
	s_or_b64 exec, exec, s[54:55]
	s_waitcnt vmcnt(7)
	v_lshlrev_b32_e32 v18, 16, v69
	v_and_b32_e32 v19, 0xffff0000, v69
	v_lshlrev_b32_e32 v16, 16, v68
	s_waitcnt lgkmcnt(0)
	v_and_b32_e32 v17, 0xffff0000, v68
	v_pk_fma_f32 v[14:15], v[14:15], 0.5, v[18:19] op_sel_hi:[1,0,1]
	v_pk_fma_f32 v[16:17], v[12:13], 0.5, v[16:17] op_sel_hi:[1,0,1]
	v_pk_mul_f32 v[18:19], v[14:15], v[14:15]
	v_cvt_pk_bf16_f32 v12, v16, v17
	v_cvt_pk_bf16_f32 v13, v14, v15
	v_lshlrev_b32_e32 v14, 16, v70
	v_and_b32_e32 v15, 0xffff0000, v70
	v_pk_fma_f32 v[16:17], v[16:17], v[16:17], v[18:19]
	v_pk_fma_f32 v[8:9], v[8:9], 0.5, v[14:15] op_sel_hi:[1,0,1]
	s_nop 0
	v_pk_fma_f32 v[16:17], v[8:9], v[8:9], v[16:17]
	v_cvt_pk_bf16_f32 v14, v8, v9
	v_lshlrev_b32_e32 v8, 16, v71
	v_and_b32_e32 v9, 0xffff0000, v71
	v_pk_fma_f32 v[8:9], v[10:11], 0.5, v[8:9] op_sel_hi:[1,0,1]
	s_nop 0
	v_pk_fma_f32 v[10:11], v[8:9], v[8:9], v[16:17]
	v_cvt_pk_bf16_f32 v15, v8, v9
	s_waitcnt vmcnt(6)
	v_lshlrev_b32_e32 v8, 16, v64
	v_and_b32_e32 v9, 0xffff0000, v64
	v_pk_fma_f32 v[4:5], v[4:5], 0.5, v[8:9] op_sel_hi:[1,0,1]
	s_nop 0
	v_pk_fma_f32 v[8:9], v[4:5], v[4:5], v[10:11]
	v_lshlrev_b32_e32 v10, 16, v65
	v_and_b32_e32 v11, 0xffff0000, v65
	v_pk_fma_f32 v[6:7], v[6:7], 0.5, v[10:11] op_sel_hi:[1,0,1]
	v_lshlrev_b32_e32 v10, 16, v66
	v_and_b32_e32 v11, 0xffff0000, v66
	v_pk_fma_f32 v[8:9], v[6:7], v[6:7], v[8:9]
	v_pk_fma_f32 v[10:11], v[0:1], 0.5, v[10:11] op_sel_hi:[1,0,1]
	s_nop 0
	v_pk_fma_f32 v[0:1], v[10:11], v[10:11], v[8:9]
	v_lshlrev_b32_e32 v8, 16, v67
	v_and_b32_e32 v9, 0xffff0000, v67
	v_pk_fma_f32 v[8:9], v[2:3], 0.5, v[8:9] op_sel_hi:[1,0,1]
	s_nop 0
	v_pk_fma_f32 v[0:1], v[8:9], v[8:9], v[0:1]
	s_nop 0
	v_add_f32_e32 v3, v0, v1
	ds_bpermute_b32 v18, v193, v3
	v_lshl_add_u64 v[0:1], s[22:23], 0, v[88:89]
	v_lshl_add_u64 v[16:17], v[172:173], 1, v[0:1]
	global_store_dwordx4 v[16:17], v[12:15], off sc1
	v_cvt_pk_bf16_f32 v2, v4, v5
	s_waitcnt lgkmcnt(0)
	v_add_f32_e32 v0, v3, v18
	ds_bpermute_b32 v1, v112, v0
	v_cvt_pk_bf16_f32 v3, v6, v7
	v_cvt_pk_bf16_f32 v4, v10, v11
	v_cvt_pk_bf16_f32 v5, v8, v9
	global_store_dwordx4 v[16:17], v[2:5], off offset:256 sc1
	s_and_saveexec_b64 s[54:55], s[8:9]
	s_cbranch_execz .LBB0_178
	s_waitcnt lgkmcnt(0)
	v_add_f32_e32 v0, v0, v1
	ds_write_b32 v188, v0 offset:2816
.LBB0_178:
	s_or_b64 exec, exec, s[54:55]
	s_waitcnt lgkmcnt(0)
	s_barrier
	s_and_saveexec_b64 s[54:55], s[10:11]
	s_cbranch_execz .LBB0_180
	s_waitcnt lgkmcnt(0)
	ds_read_b128 v[0:3], v192
	v_or_b32_e32 v4, s17, v157
	v_ashrrev_i32_e32 v5, 31, v4
	s_ashr_i32 s17, s16, 31
	s_waitcnt lgkmcnt(0)
	v_mov_b32_e32 v6, v1
	v_mov_b32_e32 v7, v2
	v_mov_b32_e32 v1, v3
	v_pk_add_f32 v[0:1], v[6:7], v[0:1]
	s_nop 0
	v_add_f32_e32 v2, v0, v1
	v_lshl_add_u64 v[0:1], v[4:5], 4, s[26:27]
	v_lshl_add_u64 v[0:1], s[16:17], 2, v[0:1]
	global_store_dword v[0:1], v2, off sc1

.LBB0_443:
	s_lshl_b32 s15, s58, 8
	v_lshl_or_b32 v172, s14, 8, v187
	v_add_u32_e32 v176, s15, v185
	v_ashrrev_i32_e32 v173, 31, v172
	v_lshlrev_b64 v[202:203], 1, v[172:173]
	v_ashrrev_i32_e32 v177, 31, v176
	v_lshl_add_u64 v[174:175], s[20:21], 0, v[202:203]
	v_lshlrev_b64 v[204:205], 11, v[176:177]
	v_lshl_add_u64 v[128:129], v[174:175], 0, v[204:205]
	global_load_dwordx4 v[194:197], v[128:129], off
	global_load_dwordx4 v[198:201], v[128:129], off offset:256
	v_or_b32_e32 v128, 16, v176
	v_or_b32_e32 v130, 32, v176
	v_or_b32_e32 v132, 48, v176
	v_ashrrev_i32_e32 v129, 31, v128
	v_ashrrev_i32_e32 v131, 31, v130
	v_ashrrev_i32_e32 v133, 31, v132
	v_lshlrev_b64 v[182:183], 11, v[128:129]
	v_lshlrev_b64 v[180:181], 11, v[130:131]
	v_lshlrev_b64 v[178:179], 11, v[132:133]
	v_lshl_add_u64 v[128:129], v[174:175], 0, v[182:183]
	v_lshl_add_u64 v[130:131], v[174:175], 0, v[180:181]
	v_lshl_add_u64 v[206:207], v[174:175], 0, v[178:179]
	global_load_dwordx4 v[148:151], v[128:129], off
	global_load_dwordx4 v[144:147], v[128:129], off offset:256
	global_load_dwordx4 v[140:143], v[130:131], off
	global_load_dwordx4 v[136:139], v[130:131], off offset:256
	global_load_dwordx4 v[132:135], v[206:207], off
	s_nop 0
	global_load_dwordx4 v[128:131], v[206:207], off offset:256
	v_and_b32_e32 v206, 64, v159
	v_xor_b32_e32 v193, 16, v159
	v_add_u32_e32 v206, 64, v206
	v_xor_b32_e32 v207, 32, v159
	v_cmp_lt_i32_e32 vcc, v193, v206
	v_lshl_add_u64 v[204:205], s[20:21], 0, v[204:205]
	v_lshl_add_u64 v[202:203], v[204:205], 0, v[202:203]
	v_cndmask_b32_e32 v193, v159, v193, vcc
	v_cmp_lt_i32_e32 vcc, v207, v206
	v_lshlrev_b32_e32 v193, 2, v193
	s_waitcnt vmcnt(0)
	v_lshlrev_b32_e32 v204, 16, v194
	v_and_b32_e32 v205, 0xffff0000, v194
	v_lshlrev_b32_e32 v194, 16, v195
	v_and_b32_e32 v195, 0xffff0000, v195
	v_cndmask_b32_e32 v212, v159, v207, vcc
	v_lshlrev_b32_e32 v206, 16, v196
	v_and_b32_e32 v207, 0xffff0000, v196
	v_lshlrev_b32_e32 v196, 16, v197
	v_and_b32_e32 v197, 0xffff0000, v197
	v_lshlrev_b32_e32 v210, 16, v200
	v_and_b32_e32 v211, 0xffff0000, v200
	v_lshlrev_b32_e32 v200, 16, v201
	v_and_b32_e32 v201, 0xffff0000, v201
	v_pk_add_f32 v[126:127], v[126:127], v[194:195]
	v_pk_add_f32 v[124:125], v[124:125], v[204:205]
	v_pk_add_f32 v[122:123], v[122:123], v[196:197]
	v_pk_add_f32 v[196:197], v[114:115], v[200:201]
	v_pk_mul_f32 v[114:115], v[126:127], v[126:127]
	v_pk_add_f32 v[120:121], v[120:121], v[206:207]
	v_pk_fma_f32 v[114:115], v[124:125], v[124:125], v[114:115]
	v_lshlrev_b32_e32 v208, 16, v198
	v_and_b32_e32 v209, 0xffff0000, v198
	v_pk_fma_f32 v[114:115], v[120:121], v[120:121], v[114:115]
	v_lshlrev_b32_e32 v198, 16, v199
	v_and_b32_e32 v199, 0xffff0000, v199
	v_pk_add_f32 v[116:117], v[116:117], v[208:209]
	v_pk_fma_f32 v[114:115], v[122:123], v[122:123], v[114:115]
	v_pk_add_f32 v[118:119], v[118:119], v[198:199]
	v_pk_fma_f32 v[114:115], v[116:117], v[116:117], v[114:115]
	v_pk_add_f32 v[194:195], v[112:113], v[210:211]
	v_pk_fma_f32 v[114:115], v[118:119], v[118:119], v[114:115]
	v_cvt_pk_bf16_f32 v112, v124, v125
	v_cvt_pk_bf16_f32 v113, v126, v127
	s_nop 0
	v_pk_fma_f32 v[114:115], v[194:195], v[194:195], v[114:115]
	s_nop 0
	v_pk_fma_f32 v[114:115], v[196:197], v[196:197], v[114:115]
	s_nop 0
	v_add_f32_e32 v124, v114, v115
	ds_bpermute_b32 v125, v193, v124
	v_cvt_pk_bf16_f32 v114, v120, v121
	v_cvt_pk_bf16_f32 v115, v122, v123
	global_store_dwordx4 v[202:203], v[112:115], off sc1
	v_cvt_pk_bf16_f32 v116, v116, v117
	v_cvt_pk_bf16_f32 v117, v118, v119
	v_cvt_pk_bf16_f32 v118, v194, v195
	v_cvt_pk_bf16_f32 v119, v196, v197
	global_store_dwordx4 v[202:203], v[116:119], off offset:256 sc1
	s_waitcnt lgkmcnt(0)
	v_add_f32_e32 v113, v124, v125
	v_lshlrev_b32_e32 v112, 2, v212
	ds_bpermute_b32 v114, v112, v113
	s_and_saveexec_b64 s[58:59], s[8:9]
	s_cbranch_execz .LBB0_445
	s_waitcnt lgkmcnt(0)
	v_add_f32_e32 v113, v113, v114
	ds_write_b32 v188, v113
.LBB0_445:
	s_or_b64 exec, exec, s[58:59]
	v_lshlrev_b32_e32 v116, 16, v149
	v_and_b32_e32 v117, 0xffff0000, v149
	s_waitcnt lgkmcnt(0)
	v_lshlrev_b32_e32 v114, 16, v148
	v_and_b32_e32 v115, 0xffff0000, v148
	v_pk_add_f32 v[110:111], v[110:111], v[116:117]
	v_pk_add_f32 v[114:115], v[108:109], v[114:115]
	v_pk_mul_f32 v[116:117], v[110:111], v[110:111]
	v_cvt_pk_bf16_f32 v108, v114, v115
	v_cvt_pk_bf16_f32 v109, v110, v111
	v_lshlrev_b32_e32 v110, 16, v150
	v_and_b32_e32 v111, 0xffff0000, v150
	v_pk_fma_f32 v[114:115], v[114:115], v[114:115], v[116:117]
	v_pk_add_f32 v[104:105], v[104:105], v[110:111]
	s_nop 0
	v_pk_fma_f32 v[114:115], v[104:105], v[104:105], v[114:115]
	v_cvt_pk_bf16_f32 v110, v104, v105
	v_lshlrev_b32_e32 v104, 16, v151
	v_and_b32_e32 v105, 0xffff0000, v151
	v_pk_add_f32 v[104:105], v[106:107], v[104:105]
	s_nop 0
	v_pk_fma_f32 v[106:107], v[104:105], v[104:105], v[114:115]
	v_cvt_pk_bf16_f32 v111, v104, v105
	v_lshlrev_b32_e32 v104, 16, v144
	v_and_b32_e32 v105, 0xffff0000, v144
	v_pk_add_f32 v[100:101], v[100:101], v[104:105]
	s_nop 0
	v_pk_fma_f32 v[104:105], v[100:101], v[100:101], v[106:107]
	v_lshlrev_b32_e32 v106, 16, v145
	v_and_b32_e32 v107, 0xffff0000, v145
	v_pk_add_f32 v[102:103], v[102:103], v[106:107]
	v_lshlrev_b32_e32 v106, 16, v146
	v_and_b32_e32 v107, 0xffff0000, v146
	v_pk_fma_f32 v[104:105], v[102:103], v[102:103], v[104:105]
	v_pk_add_f32 v[106:107], v[96:97], v[106:107]
	s_nop 0
	v_pk_fma_f32 v[96:97], v[106:107], v[106:107], v[104:105]
	v_lshlrev_b32_e32 v104, 16, v147
	v_and_b32_e32 v105, 0xffff0000, v147
	v_pk_add_f32 v[104:105], v[98:99], v[104:105]
	s_nop 0
	v_pk_fma_f32 v[96:97], v[104:105], v[104:105], v[96:97]
	s_nop 0
	v_add_f32_e32 v99, v96, v97
	ds_bpermute_b32 v113, v193, v99
	v_lshl_add_u64 v[96:97], s[20:21], 0, v[182:183]
	v_lshl_add_u64 v[114:115], v[172:173], 1, v[96:97]
	global_store_dwordx4 v[114:115], v[108:111], off sc1
	v_cvt_pk_bf16_f32 v98, v100, v101
	s_waitcnt lgkmcnt(0)
	v_add_f32_e32 v96, v99, v113
	ds_bpermute_b32 v97, v112, v96
	v_cvt_pk_bf16_f32 v99, v102, v103
	v_cvt_pk_bf16_f32 v100, v106, v107
	v_cvt_pk_bf16_f32 v101, v104, v105
	global_store_dwordx4 v[114:115], v[98:101], off offset:256 sc1
	s_and_saveexec_b64 s[58:59], s[8:9]
	s_cbranch_execz .LBB0_447
	s_waitcnt lgkmcnt(0)
	v_add_f32_e32 v96, v96, v97
	ds_write_b32 v188, v96 offset:256
.LBB0_447:
	s_or_b64 exec, exec, s[58:59]
	v_lshlrev_b32_e32 v98, 16, v141
	v_and_b32_e32 v99, 0xffff0000, v141
	v_lshlrev_b32_e32 v96, 16, v140
	s_waitcnt lgkmcnt(0)
	v_and_b32_e32 v97, 0xffff0000, v140
	v_pk_add_f32 v[94:95], v[94:95], v[98:99]
	v_pk_add_f32 v[96:97], v[92:93], v[96:97]
	v_pk_mul_f32 v[98:99], v[94:95], v[94:95]
	v_cvt_pk_bf16_f32 v92, v96, v97
	v_cvt_pk_bf16_f32 v93, v94, v95
	v_lshlrev_b32_e32 v94, 16, v142
	v_and_b32_e32 v95, 0xffff0000, v142
	v_pk_fma_f32 v[96:97], v[96:97], v[96:97], v[98:99]
	v_pk_add_f32 v[88:89], v[88:89], v[94:95]
	s_nop 0
	v_pk_fma_f32 v[96:97], v[88:89], v[88:89], v[96:97]
	v_cvt_pk_bf16_f32 v94, v88, v89
	v_lshlrev_b32_e32 v88, 16, v143
	v_and_b32_e32 v89, 0xffff0000, v143
	v_pk_add_f32 v[88:89], v[90:91], v[88:89]
	s_nop 0
	v_pk_fma_f32 v[90:91], v[88:89], v[88:89], v[96:97]
	v_cvt_pk_bf16_f32 v95, v88, v89
	v_lshlrev_b32_e32 v88, 16, v136
	v_and_b32_e32 v89, 0xffff0000, v136
	v_pk_add_f32 v[84:85], v[84:85], v[88:89]
	s_nop 0
	v_pk_fma_f32 v[88:89], v[84:85], v[84:85], v[90:91]
	v_lshlrev_b32_e32 v90, 16, v137
	v_and_b32_e32 v91, 0xffff0000, v137
	v_pk_add_f32 v[86:87], v[86:87], v[90:91]
	v_lshlrev_b32_e32 v90, 16, v138
	v_and_b32_e32 v91, 0xffff0000, v138
	v_pk_fma_f32 v[88:89], v[86:87], v[86:87], v[88:89]
	v_pk_add_f32 v[90:91], v[80:81], v[90:91]
	s_nop 0
	v_pk_fma_f32 v[80:81], v[90:91], v[90:91], v[88:89]
	v_lshlrev_b32_e32 v88, 16, v139
	v_and_b32_e32 v89, 0xffff0000, v139
	v_pk_add_f32 v[88:89], v[82:83], v[88:89]
	s_nop 0
	v_pk_fma_f32 v[80:81], v[88:89], v[88:89], v[80:81]
	s_nop 0
	v_add_f32_e32 v83, v80, v81
	ds_bpermute_b32 v98, v193, v83
	v_lshl_add_u64 v[80:81], s[20:21], 0, v[180:181]
	v_lshl_add_u64 v[96:97], v[172:173], 1, v[80:81]
	global_store_dwordx4 v[96:97], v[92:95], off sc1
	v_cvt_pk_bf16_f32 v82, v84, v85
	s_waitcnt lgkmcnt(0)
	v_add_f32_e32 v80, v83, v98
	ds_bpermute_b32 v81, v112, v80
	v_cvt_pk_bf16_f32 v83, v86, v87
	v_cvt_pk_bf16_f32 v84, v90, v91
	v_cvt_pk_bf16_f32 v85, v88, v89
	global_store_dwordx4 v[96:97], v[82:85], off offset:256 sc1
	s_and_saveexec_b64 s[58:59], s[8:9]
	s_cbranch_execz .LBB0_449
	s_waitcnt lgkmcnt(0)
	v_add_f32_e32 v80, v80, v81
	ds_write_b32 v188, v80 offset:512
.LBB0_449:
	s_or_b64 exec, exec, s[58:59]
	v_lshlrev_b32_e32 v82, 16, v133
	v_and_b32_e32 v83, 0xffff0000, v133
	v_lshlrev_b32_e32 v80, 16, v132
	s_waitcnt lgkmcnt(0)
	v_and_b32_e32 v81, 0xffff0000, v132
	v_pk_add_f32 v[78:79], v[78:79], v[82:83]
	v_pk_add_f32 v[80:81], v[76:77], v[80:81]
	v_pk_mul_f32 v[82:83], v[78:79], v[78:79]
	v_cvt_pk_bf16_f32 v76, v80, v81
	v_cvt_pk_bf16_f32 v77, v78, v79
	v_lshlrev_b32_e32 v78, 16, v134
	v_and_b32_e32 v79, 0xffff0000, v134
	v_pk_fma_f32 v[80:81], v[80:81], v[80:81], v[82:83]
	v_pk_add_f32 v[72:73], v[72:73], v[78:79]
	s_nop 0
	v_pk_fma_f32 v[80:81], v[72:73], v[72:73], v[80:81]
	v_cvt_pk_bf16_f32 v78, v72, v73
	v_lshlrev_b32_e32 v72, 16, v135
	v_and_b32_e32 v73, 0xffff0000, v135
	v_pk_add_f32 v[72:73], v[74:75], v[72:73]
	s_nop 0
	v_pk_fma_f32 v[74:75], v[72:73], v[72:73], v[80:81]
	v_cvt_pk_bf16_f32 v79, v72, v73
	v_lshlrev_b32_e32 v72, 16, v128
	v_and_b32_e32 v73, 0xffff0000, v128
	v_pk_add_f32 v[68:69], v[68:69], v[72:73]
	s_nop 0
	v_pk_fma_f32 v[72:73], v[68:69], v[68:69], v[74:75]
	v_lshlrev_b32_e32 v74, 16, v129
	v_and_b32_e32 v75, 0xffff0000, v129
	v_pk_add_f32 v[70:71], v[70:71], v[74:75]
	v_lshlrev_b32_e32 v74, 16, v130
	v_and_b32_e32 v75, 0xffff0000, v130
	v_pk_fma_f32 v[72:73], v[70:71], v[70:71], v[72:73]
	v_pk_add_f32 v[74:75], v[64:65], v[74:75]
	s_nop 0
	v_pk_fma_f32 v[64:65], v[74:75], v[74:75], v[72:73]
	v_lshlrev_b32_e32 v72, 16, v131
	v_and_b32_e32 v73, 0xffff0000, v131
	v_pk_add_f32 v[72:73], v[66:67], v[72:73]
	s_nop 0
	v_pk_fma_f32 v[64:65], v[72:73], v[72:73], v[64:65]
	s_nop 0
	v_add_f32_e32 v67, v64, v65
	ds_bpermute_b32 v82, v193, v67
	v_lshl_add_u64 v[64:65], s[20:21], 0, v[178:179]
	v_lshl_add_u64 v[80:81], v[172:173], 1, v[64:65]
	global_store_dwordx4 v[80:81], v[76:79], off sc1
	v_cvt_pk_bf16_f32 v66, v68, v69
	s_waitcnt lgkmcnt(0)
	v_add_f32_e32 v64, v67, v82
	ds_bpermute_b32 v65, v112, v64
	v_cvt_pk_bf16_f32 v67, v70, v71
	v_cvt_pk_bf16_f32 v68, v74, v75
	v_cvt_pk_bf16_f32 v69, v72, v73
	global_store_dwordx4 v[80:81], v[66:69], off offset:256 sc1
	s_and_saveexec_b64 s[58:59], s[8:9]
	s_cbranch_execz .LBB0_451
	s_waitcnt lgkmcnt(0)
	v_add_f32_e32 v64, v64, v65
	ds_write_b32 v188, v64 offset:768
.LBB0_451:
	s_or_b64 exec, exec, s[58:59]
	s_waitcnt lgkmcnt(0)
	v_lshlrev_b64 v[64:65], 11, v[176:177]
	v_lshl_add_u64 v[102:103], v[64:65], 0, s[30:31]
	v_lshl_add_u64 v[66:67], v[174:175], 0, v[102:103]
	global_load_dwordx4 v[94:97], v[66:67], off
	global_load_dwordx4 v[98:101], v[66:67], off offset:256
	v_lshl_add_u64 v[92:93], v[64:65], 0, s[44:45]
	v_lshl_add_u64 v[90:91], v[64:65], 0, s[46:47]
	v_lshl_add_u64 v[88:89], v[64:65], 0, s[48:49]
	v_lshl_add_u64 v[64:65], v[174:175], 0, v[92:93]
	v_lshl_add_u64 v[66:67], v[174:175], 0, v[90:91]
	v_lshl_add_u64 v[104:105], v[174:175], 0, v[88:89]
	global_load_dwordx4 v[84:87], v[64:65], off
	global_load_dwordx4 v[80:83], v[64:65], off offset:256
	global_load_dwordx4 v[76:79], v[66:67], off
	global_load_dwordx4 v[72:75], v[66:67], off offset:256
	global_load_dwordx4 v[68:71], v[104:105], off
	s_nop 0
	global_load_dwordx4 v[64:67], v[104:105], off offset:256
	s_waitcnt vmcnt(7)
	v_lshlrev_b32_e32 v104, 16, v94
	v_and_b32_e32 v105, 0xffff0000, v94
	v_lshlrev_b32_e32 v94, 16, v95
	v_and_b32_e32 v95, 0xffff0000, v95
	v_lshlrev_b32_e32 v106, 16, v96
	v_and_b32_e32 v107, 0xffff0000, v96
	v_lshlrev_b32_e32 v96, 16, v97
	v_and_b32_e32 v97, 0xffff0000, v97
	s_waitcnt vmcnt(6)
	v_lshlrev_b32_e32 v108, 16, v98
	v_and_b32_e32 v109, 0xffff0000, v98
	v_lshlrev_b32_e32 v98, 16, v99
	v_and_b32_e32 v99, 0xffff0000, v99
	v_lshlrev_b32_e32 v110, 16, v100
	v_and_b32_e32 v111, 0xffff0000, v100
	v_pk_add_f32 v[62:63], v[62:63], v[94:95]
	v_pk_add_f32 v[60:61], v[60:61], v[104:105]
	v_pk_add_f32 v[58:59], v[58:59], v[96:97]
	v_pk_add_f32 v[96:97], v[54:55], v[98:99]
	v_pk_add_f32 v[98:99], v[48:49], v[110:111]
	v_pk_mul_f32 v[48:49], v[62:63], v[62:63]
	v_pk_add_f32 v[56:57], v[56:57], v[106:107]
	v_pk_fma_f32 v[48:49], v[60:61], v[60:61], v[48:49]
	v_pk_add_f32 v[94:95], v[52:53], v[108:109]
	v_pk_fma_f32 v[48:49], v[56:57], v[56:57], v[48:49]
	v_lshlrev_b32_e32 v100, 16, v101
	v_pk_fma_f32 v[48:49], v[58:59], v[58:59], v[48:49]
	v_and_b32_e32 v101, 0xffff0000, v101
	v_pk_fma_f32 v[48:49], v[94:95], v[94:95], v[48:49]
	v_cvt_pk_bf16_f32 v52, v60, v61
	v_cvt_pk_bf16_f32 v53, v62, v63
	v_cvt_pk_bf16_f32 v54, v56, v57
	v_pk_add_f32 v[56:57], v[50:51], v[100:101]
	v_pk_fma_f32 v[48:49], v[96:97], v[96:97], v[48:49]
	v_cvt_pk_bf16_f32 v55, v58, v59
	s_nop 0
	v_pk_fma_f32 v[48:49], v[98:99], v[98:99], v[48:49]
	s_nop 0
	v_pk_fma_f32 v[48:49], v[56:57], v[56:57], v[48:49]
	s_nop 0
	v_add_f32_e32 v51, v48, v49
	ds_bpermute_b32 v60, v193, v51
	v_lshl_add_u64 v[48:49], s[20:21], 0, v[102:103]
	v_lshl_add_u64 v[58:59], v[172:173], 1, v[48:49]
	global_store_dwordx4 v[58:59], v[52:55], off sc1
	v_cvt_pk_bf16_f32 v50, v94, v95
	s_waitcnt lgkmcnt(0)
	v_add_f32_e32 v48, v51, v60
	ds_bpermute_b32 v49, v112, v48
	v_cvt_pk_bf16_f32 v51, v96, v97
	v_cvt_pk_bf16_f32 v52, v98, v99
	v_cvt_pk_bf16_f32 v53, v56, v57
	global_store_dwordx4 v[58:59], v[50:53], off offset:256 sc1
	s_and_saveexec_b64 s[58:59], s[8:9]
	s_cbranch_execz .LBB0_453
	s_waitcnt lgkmcnt(0)
	v_add_f32_e32 v48, v48, v49
	ds_write_b32 v188, v48 offset:2048
.LBB0_453:
	s_or_b64 exec, exec, s[58:59]
	s_waitcnt vmcnt(7)
	v_lshlrev_b32_e32 v50, 16, v85
	v_and_b32_e32 v51, 0xffff0000, v85
	v_lshlrev_b32_e32 v48, 16, v84
	s_waitcnt lgkmcnt(0)
	v_and_b32_e32 v49, 0xffff0000, v84
	v_pk_add_f32 v[46:47], v[46:47], v[50:51]
	v_pk_add_f32 v[48:49], v[44:45], v[48:49]
	v_pk_mul_f32 v[50:51], v[46:47], v[46:47]
	v_cvt_pk_bf16_f32 v44, v48, v49
	v_cvt_pk_bf16_f32 v45, v46, v47
	v_lshlrev_b32_e32 v46, 16, v86
	v_and_b32_e32 v47, 0xffff0000, v86
	v_pk_fma_f32 v[48:49], v[48:49], v[48:49], v[50:51]
	v_pk_add_f32 v[40:41], v[40:41], v[46:47]
	s_nop 0
	v_pk_fma_f32 v[48:49], v[40:41], v[40:41], v[48:49]
	v_cvt_pk_bf16_f32 v46, v40, v41
	v_lshlrev_b32_e32 v40, 16, v87
	v_and_b32_e32 v41, 0xffff0000, v87
	v_pk_add_f32 v[40:41], v[42:43], v[40:41]
	s_nop 0
	v_pk_fma_f32 v[42:43], v[40:41], v[40:41], v[48:49]
	v_cvt_pk_bf16_f32 v47, v40, v41
	s_waitcnt vmcnt(6)
	v_lshlrev_b32_e32 v40, 16, v80
	v_and_b32_e32 v41, 0xffff0000, v80
	v_pk_add_f32 v[36:37], v[36:37], v[40:41]
	s_nop 0
	v_pk_fma_f32 v[40:41], v[36:37], v[36:37], v[42:43]
	v_lshlrev_b32_e32 v42, 16, v81
	v_and_b32_e32 v43, 0xffff0000, v81
	v_pk_add_f32 v[38:39], v[38:39], v[42:43]
	v_lshlrev_b32_e32 v42, 16, v82
	v_and_b32_e32 v43, 0xffff0000, v82
	v_pk_fma_f32 v[40:41], v[38:39], v[38:39], v[40:41]
	v_pk_add_f32 v[42:43], v[32:33], v[42:43]
	s_nop 0
	v_pk_fma_f32 v[32:33], v[42:43], v[42:43], v[40:41]
	v_lshlrev_b32_e32 v40, 16, v83
	v_and_b32_e32 v41, 0xffff0000, v83
	v_pk_add_f32 v[40:41], v[34:35], v[40:41]
	s_nop 0
	v_pk_fma_f32 v[32:33], v[40:41], v[40:41], v[32:33]
	s_nop 0
	v_add_f32_e32 v35, v32, v33
	ds_bpermute_b32 v50, v193, v35
	v_lshl_add_u64 v[32:33], s[20:21], 0, v[92:93]
	v_lshl_add_u64 v[48:49], v[172:173], 1, v[32:33]
	global_store_dwordx4 v[48:49], v[44:47], off sc1
	v_cvt_pk_bf16_f32 v34, v36, v37
	s_waitcnt lgkmcnt(0)
	v_add_f32_e32 v32, v35, v50
	ds_bpermute_b32 v33, v112, v32
	v_cvt_pk_bf16_f32 v35, v38, v39
	v_cvt_pk_bf16_f32 v36, v42, v43
	v_cvt_pk_bf16_f32 v37, v40, v41
	global_store_dwordx4 v[48:49], v[34:37], off offset:256 sc1
	s_and_saveexec_b64 s[58:59], s[8:9]
	s_cbranch_execz .LBB0_455
	s_waitcnt lgkmcnt(0)
	v_add_f32_e32 v32, v32, v33
	ds_write_b32 v188, v32 offset:2304
.LBB0_455:
	s_or_b64 exec, exec, s[58:59]
	s_waitcnt vmcnt(7)
	v_lshlrev_b32_e32 v34, 16, v77
	v_and_b32_e32 v35, 0xffff0000, v77
	v_lshlrev_b32_e32 v32, 16, v76
	s_waitcnt lgkmcnt(0)
	v_and_b32_e32 v33, 0xffff0000, v76
	v_pk_add_f32 v[30:31], v[30:31], v[34:35]
	v_pk_add_f32 v[32:33], v[28:29], v[32:33]
	v_pk_mul_f32 v[34:35], v[30:31], v[30:31]
	v_cvt_pk_bf16_f32 v28, v32, v33
	v_cvt_pk_bf16_f32 v29, v30, v31
	v_lshlrev_b32_e32 v30, 16, v78
	v_and_b32_e32 v31, 0xffff0000, v78
	v_pk_fma_f32 v[32:33], v[32:33], v[32:33], v[34:35]
	v_pk_add_f32 v[24:25], v[24:25], v[30:31]
	s_nop 0
	v_pk_fma_f32 v[32:33], v[24:25], v[24:25], v[32:33]
	v_cvt_pk_bf16_f32 v30, v24, v25
	v_lshlrev_b32_e32 v24, 16, v79
	v_and_b32_e32 v25, 0xffff0000, v79
	v_pk_add_f32 v[24:25], v[26:27], v[24:25]
	s_nop 0
	v_pk_fma_f32 v[26:27], v[24:25], v[24:25], v[32:33]
	v_cvt_pk_bf16_f32 v31, v24, v25
	s_waitcnt vmcnt(6)
	v_lshlrev_b32_e32 v24, 16, v72
	v_and_b32_e32 v25, 0xffff0000, v72
	v_pk_add_f32 v[20:21], v[20:21], v[24:25]
	s_nop 0
	v_pk_fma_f32 v[24:25], v[20:21], v[20:21], v[26:27]
	v_lshlrev_b32_e32 v26, 16, v73
	v_and_b32_e32 v27, 0xffff0000, v73
	v_pk_add_f32 v[22:23], v[22:23], v[26:27]
	v_lshlrev_b32_e32 v26, 16, v74
	v_and_b32_e32 v27, 0xffff0000, v74
	v_pk_fma_f32 v[24:25], v[22:23], v[22:23], v[24:25]
	v_pk_add_f32 v[26:27], v[16:17], v[26:27]
	s_nop 0
	v_pk_fma_f32 v[16:17], v[26:27], v[26:27], v[24:25]
	v_lshlrev_b32_e32 v24, 16, v75
	v_and_b32_e32 v25, 0xffff0000, v75
	v_pk_add_f32 v[24:25], v[18:19], v[24:25]
	s_nop 0
	v_pk_fma_f32 v[16:17], v[24:25], v[24:25], v[16:17]
	s_nop 0
	v_add_f32_e32 v19, v16, v17
	ds_bpermute_b32 v34, v193, v19
	v_lshl_add_u64 v[16:17], s[20:21], 0, v[90:91]
	v_lshl_add_u64 v[32:33], v[172:173], 1, v[16:17]
	global_store_dwordx4 v[32:33], v[28:31], off sc1
	v_cvt_pk_bf16_f32 v18, v20, v21
	s_waitcnt lgkmcnt(0)
	v_add_f32_e32 v16, v19, v34
	ds_bpermute_b32 v17, v112, v16
	v_cvt_pk_bf16_f32 v19, v22, v23
	v_cvt_pk_bf16_f32 v20, v26, v27
	v_cvt_pk_bf16_f32 v21, v24, v25
	global_store_dwordx4 v[32:33], v[18:21], off offset:256 sc1
	s_and_saveexec_b64 s[58:59], s[8:9]
	s_cbranch_execz .LBB0_457
	s_waitcnt lgkmcnt(0)
	v_add_f32_e32 v16, v16, v17
	ds_write_b32 v188, v16 offset:2560
.LBB0_457:
	s_or_b64 exec, exec, s[58:59]
	s_waitcnt vmcnt(7)
	v_lshlrev_b32_e32 v18, 16, v69
	v_and_b32_e32 v19, 0xffff0000, v69
	v_lshlrev_b32_e32 v16, 16, v68
	s_waitcnt lgkmcnt(0)
	v_and_b32_e32 v17, 0xffff0000, v68
	v_pk_add_f32 v[14:15], v[14:15], v[18:19]
	v_pk_add_f32 v[16:17], v[12:13], v[16:17]
	v_pk_mul_f32 v[18:19], v[14:15], v[14:15]
	v_cvt_pk_bf16_f32 v12, v16, v17
	v_cvt_pk_bf16_f32 v13, v14, v15
	v_lshlrev_b32_e32 v14, 16, v70
	v_and_b32_e32 v15, 0xffff0000, v70
	v_pk_fma_f32 v[16:17], v[16:17], v[16:17], v[18:19]
	v_pk_add_f32 v[8:9], v[8:9], v[14:15]
	s_nop 0
	v_pk_fma_f32 v[16:17], v[8:9], v[8:9], v[16:17]
	v_cvt_pk_bf16_f32 v14, v8, v9
	v_lshlrev_b32_e32 v8, 16, v71
	v_and_b32_e32 v9, 0xffff0000, v71
	v_pk_add_f32 v[8:9], v[10:11], v[8:9]
	s_nop 0
	v_pk_fma_f32 v[10:11], v[8:9], v[8:9], v[16:17]
	v_cvt_pk_bf16_f32 v15, v8, v9
	s_waitcnt vmcnt(6)
	v_lshlrev_b32_e32 v8, 16, v64
	v_and_b32_e32 v9, 0xffff0000, v64
	v_pk_add_f32 v[4:5], v[4:5], v[8:9]
	s_nop 0
	v_pk_fma_f32 v[8:9], v[4:5], v[4:5], v[10:11]
	v_lshlrev_b32_e32 v10, 16, v65
	v_and_b32_e32 v11, 0xffff0000, v65
	v_pk_add_f32 v[6:7], v[6:7], v[10:11]
	v_lshlrev_b32_e32 v10, 16, v66
	v_and_b32_e32 v11, 0xffff0000, v66
	v_pk_fma_f32 v[8:9], v[6:7], v[6:7], v[8:9]
	v_pk_add_f32 v[10:11], v[0:1], v[10:11]
	s_nop 0
	v_pk_fma_f32 v[0:1], v[10:11], v[10:11], v[8:9]
	v_lshlrev_b32_e32 v8, 16, v67
	v_and_b32_e32 v9, 0xffff0000, v67
	v_pk_add_f32 v[8:9], v[2:3], v[8:9]
	s_nop 0
	v_pk_fma_f32 v[0:1], v[8:9], v[8:9], v[0:1]
	s_nop 0
	v_add_f32_e32 v3, v0, v1
	ds_bpermute_b32 v18, v193, v3
	v_lshl_add_u64 v[0:1], s[20:21], 0, v[88:89]
	v_lshl_add_u64 v[16:17], v[172:173], 1, v[0:1]
	global_store_dwordx4 v[16:17], v[12:15], off sc1
	v_cvt_pk_bf16_f32 v2, v4, v5
	s_waitcnt lgkmcnt(0)
	v_add_f32_e32 v0, v3, v18
	ds_bpermute_b32 v1, v112, v0
	v_cvt_pk_bf16_f32 v3, v6, v7
	v_cvt_pk_bf16_f32 v4, v10, v11
	v_cvt_pk_bf16_f32 v5, v8, v9
	global_store_dwordx4 v[16:17], v[2:5], off offset:256 sc1
	s_and_saveexec_b64 s[58:59], s[8:9]
	s_cbranch_execz .LBB0_459
	s_waitcnt lgkmcnt(0)
	v_add_f32_e32 v0, v0, v1
	ds_write_b32 v188, v0 offset:2816
.LBB0_459:
	s_or_b64 exec, exec, s[58:59]
	s_waitcnt lgkmcnt(0)
	s_barrier
	s_and_saveexec_b64 s[58:59], s[10:11]
	s_cbranch_execz .LBB0_461
	s_waitcnt lgkmcnt(0)
	ds_read_b128 v[0:3], v192
	v_or_b32_e32 v4, s15, v157
	v_ashrrev_i32_e32 v5, 31, v4
	s_ashr_i32 s15, s14, 31
	s_waitcnt lgkmcnt(0)
	v_mov_b32_e32 v6, v1
	v_mov_b32_e32 v7, v2
	v_mov_b32_e32 v1, v3
	v_pk_add_f32 v[0:1], v[6:7], v[0:1]
	s_nop 0
	v_add_f32_e32 v2, v0, v1
	v_lshl_add_u64 v[0:1], v[4:5], 4, s[22:23]
	v_lshl_add_u64 v[0:1], s[14:15], 2, v[0:1]
	global_store_dword v[0:1], v2, off sc1

.LBB0_613:
	s_lshl_b32 s21, s21, 8
	v_lshl_or_b32 v172, s20, 8, v187
	v_add_u32_e32 v176, s21, v185
	v_ashrrev_i32_e32 v173, 31, v172
	v_lshlrev_b64 v[202:203], 1, v[172:173]
	v_ashrrev_i32_e32 v177, 31, v176
	v_lshl_add_u64 v[174:175], s[24:25], 0, v[202:203]
	v_lshlrev_b64 v[204:205], 11, v[176:177]
	v_lshl_add_u64 v[128:129], v[174:175], 0, v[204:205]
	global_load_dwordx4 v[194:197], v[128:129], off
	global_load_dwordx4 v[198:201], v[128:129], off offset:256
	v_or_b32_e32 v128, 16, v176
	v_or_b32_e32 v130, 32, v176
	v_or_b32_e32 v132, 48, v176
	v_ashrrev_i32_e32 v129, 31, v128
	v_ashrrev_i32_e32 v131, 31, v130
	v_ashrrev_i32_e32 v133, 31, v132
	v_lshlrev_b64 v[182:183], 11, v[128:129]
	v_lshlrev_b64 v[180:181], 11, v[130:131]
	v_lshlrev_b64 v[178:179], 11, v[132:133]
	v_lshl_add_u64 v[128:129], v[174:175], 0, v[182:183]
	v_lshl_add_u64 v[130:131], v[174:175], 0, v[180:181]
	v_lshl_add_u64 v[206:207], v[174:175], 0, v[178:179]
	global_load_dwordx4 v[148:151], v[128:129], off
	global_load_dwordx4 v[144:147], v[128:129], off offset:256
	global_load_dwordx4 v[140:143], v[130:131], off
	global_load_dwordx4 v[136:139], v[130:131], off offset:256
	global_load_dwordx4 v[132:135], v[206:207], off
	s_nop 0
	global_load_dwordx4 v[128:131], v[206:207], off offset:256
	v_and_b32_e32 v206, 64, v159
	v_xor_b32_e32 v193, 16, v159
	v_add_u32_e32 v206, 64, v206
	v_xor_b32_e32 v207, 32, v159
	v_cmp_lt_i32_e32 vcc, v193, v206
	v_lshl_add_u64 v[204:205], s[24:25], 0, v[204:205]
	v_lshl_add_u64 v[202:203], v[204:205], 0, v[202:203]
	v_cndmask_b32_e32 v193, v159, v193, vcc
	v_cmp_lt_i32_e32 vcc, v207, v206
	v_lshlrev_b32_e32 v193, 2, v193
	s_waitcnt vmcnt(0)
	v_lshlrev_b32_e32 v204, 16, v194
	v_and_b32_e32 v205, 0xffff0000, v194
	v_lshlrev_b32_e32 v194, 16, v195
	v_and_b32_e32 v195, 0xffff0000, v195
	v_cndmask_b32_e32 v212, v159, v207, vcc
	v_lshlrev_b32_e32 v206, 16, v196
	v_and_b32_e32 v207, 0xffff0000, v196
	v_lshlrev_b32_e32 v196, 16, v197
	v_and_b32_e32 v197, 0xffff0000, v197
	v_lshlrev_b32_e32 v210, 16, v200
	v_and_b32_e32 v211, 0xffff0000, v200
	v_lshlrev_b32_e32 v200, 16, v201
	v_and_b32_e32 v201, 0xffff0000, v201
	v_pk_fma_f32 v[126:127], v[126:127], 0.5, v[194:195] op_sel_hi:[1,0,1]
	v_pk_fma_f32 v[124:125], v[124:125], 0.5, v[204:205] op_sel_hi:[1,0,1]
	v_pk_fma_f32 v[122:123], v[122:123], 0.5, v[196:197] op_sel_hi:[1,0,1]
	v_pk_fma_f32 v[196:197], v[114:115], 0.5, v[200:201] op_sel_hi:[1,0,1]
	v_pk_mul_f32 v[114:115], v[126:127], v[126:127]
	v_pk_fma_f32 v[120:121], v[120:121], 0.5, v[206:207] op_sel_hi:[1,0,1]
	v_pk_fma_f32 v[114:115], v[124:125], v[124:125], v[114:115]
	v_lshlrev_b32_e32 v208, 16, v198
	v_and_b32_e32 v209, 0xffff0000, v198
	v_pk_fma_f32 v[114:115], v[120:121], v[120:121], v[114:115]
	v_lshlrev_b32_e32 v198, 16, v199
	v_and_b32_e32 v199, 0xffff0000, v199
	v_pk_fma_f32 v[116:117], v[116:117], 0.5, v[208:209] op_sel_hi:[1,0,1]
	v_pk_fma_f32 v[114:115], v[122:123], v[122:123], v[114:115]
	v_pk_fma_f32 v[118:119], v[118:119], 0.5, v[198:199] op_sel_hi:[1,0,1]
	v_pk_fma_f32 v[114:115], v[116:117], v[116:117], v[114:115]
	v_pk_fma_f32 v[194:195], v[112:113], 0.5, v[210:211] op_sel_hi:[1,0,1]
	v_pk_fma_f32 v[114:115], v[118:119], v[118:119], v[114:115]
	v_cvt_pk_bf16_f32 v112, v124, v125
	v_cvt_pk_bf16_f32 v113, v126, v127
	s_nop 0
	v_pk_fma_f32 v[114:115], v[194:195], v[194:195], v[114:115]
	s_nop 0
	v_pk_fma_f32 v[114:115], v[196:197], v[196:197], v[114:115]
	s_nop 0
	v_add_f32_e32 v124, v114, v115
	ds_bpermute_b32 v125, v193, v124
	v_cvt_pk_bf16_f32 v114, v120, v121
	v_cvt_pk_bf16_f32 v115, v122, v123
	global_store_dwordx4 v[202:203], v[112:115], off sc1
	v_cvt_pk_bf16_f32 v116, v116, v117
	v_cvt_pk_bf16_f32 v117, v118, v119
	v_cvt_pk_bf16_f32 v118, v194, v195
	v_cvt_pk_bf16_f32 v119, v196, v197
	global_store_dwordx4 v[202:203], v[116:119], off offset:256 sc1
	s_waitcnt lgkmcnt(0)
	v_add_f32_e32 v113, v124, v125
	v_lshlrev_b32_e32 v112, 2, v212
	ds_bpermute_b32 v114, v112, v113
	s_and_saveexec_b64 s[54:55], s[10:11]
	s_cbranch_execz .LBB0_615
	s_waitcnt lgkmcnt(0)
	v_add_f32_e32 v113, v113, v114
	ds_write_b32 v188, v113
.LBB0_615:
	s_or_b64 exec, exec, s[54:55]
	v_lshlrev_b32_e32 v116, 16, v149
	v_and_b32_e32 v117, 0xffff0000, v149
	s_waitcnt lgkmcnt(0)
	v_lshlrev_b32_e32 v114, 16, v148
	v_and_b32_e32 v115, 0xffff0000, v148
	v_pk_fma_f32 v[110:111], v[110:111], 0.5, v[116:117] op_sel_hi:[1,0,1]
	v_pk_fma_f32 v[114:115], v[108:109], 0.5, v[114:115] op_sel_hi:[1,0,1]
	v_pk_mul_f32 v[116:117], v[110:111], v[110:111]
	v_cvt_pk_bf16_f32 v108, v114, v115
	v_cvt_pk_bf16_f32 v109, v110, v111
	v_lshlrev_b32_e32 v110, 16, v150
	v_and_b32_e32 v111, 0xffff0000, v150
	v_pk_fma_f32 v[114:115], v[114:115], v[114:115], v[116:117]
	v_pk_fma_f32 v[104:105], v[104:105], 0.5, v[110:111] op_sel_hi:[1,0,1]
	s_nop 0
	v_pk_fma_f32 v[114:115], v[104:105], v[104:105], v[114:115]
	v_cvt_pk_bf16_f32 v110, v104, v105
	v_lshlrev_b32_e32 v104, 16, v151
	v_and_b32_e32 v105, 0xffff0000, v151
	v_pk_fma_f32 v[104:105], v[106:107], 0.5, v[104:105] op_sel_hi:[1,0,1]
	s_nop 0
	v_pk_fma_f32 v[106:107], v[104:105], v[104:105], v[114:115]
	v_cvt_pk_bf16_f32 v111, v104, v105
	v_lshlrev_b32_e32 v104, 16, v144
	v_and_b32_e32 v105, 0xffff0000, v144
	v_pk_fma_f32 v[100:101], v[100:101], 0.5, v[104:105] op_sel_hi:[1,0,1]
	s_nop 0
	v_pk_fma_f32 v[104:105], v[100:101], v[100:101], v[106:107]
	v_lshlrev_b32_e32 v106, 16, v145
	v_and_b32_e32 v107, 0xffff0000, v145
	v_pk_fma_f32 v[102:103], v[102:103], 0.5, v[106:107] op_sel_hi:[1,0,1]
	v_lshlrev_b32_e32 v106, 16, v146
	v_and_b32_e32 v107, 0xffff0000, v146
	v_pk_fma_f32 v[104:105], v[102:103], v[102:103], v[104:105]
	v_pk_fma_f32 v[106:107], v[96:97], 0.5, v[106:107] op_sel_hi:[1,0,1]
	s_nop 0
	v_pk_fma_f32 v[96:97], v[106:107], v[106:107], v[104:105]
	v_lshlrev_b32_e32 v104, 16, v147
	v_and_b32_e32 v105, 0xffff0000, v147
	v_pk_fma_f32 v[104:105], v[98:99], 0.5, v[104:105] op_sel_hi:[1,0,1]
	s_nop 0
	v_pk_fma_f32 v[96:97], v[104:105], v[104:105], v[96:97]
	s_nop 0
	v_add_f32_e32 v99, v96, v97
	ds_bpermute_b32 v113, v193, v99
	v_lshl_add_u64 v[96:97], s[24:25], 0, v[182:183]
	v_lshl_add_u64 v[114:115], v[172:173], 1, v[96:97]
	global_store_dwordx4 v[114:115], v[108:111], off sc1
	v_cvt_pk_bf16_f32 v98, v100, v101
	s_waitcnt lgkmcnt(0)
	v_add_f32_e32 v96, v99, v113
	ds_bpermute_b32 v97, v112, v96
	v_cvt_pk_bf16_f32 v99, v102, v103
	v_cvt_pk_bf16_f32 v100, v106, v107
	v_cvt_pk_bf16_f32 v101, v104, v105
	global_store_dwordx4 v[114:115], v[98:101], off offset:256 sc1
	s_and_saveexec_b64 s[54:55], s[10:11]
	s_cbranch_execz .LBB0_617
	s_waitcnt lgkmcnt(0)
	v_add_f32_e32 v96, v96, v97
	ds_write_b32 v188, v96 offset:256
.LBB0_617:
	s_or_b64 exec, exec, s[54:55]
	v_lshlrev_b32_e32 v98, 16, v141
	v_and_b32_e32 v99, 0xffff0000, v141
	v_lshlrev_b32_e32 v96, 16, v140
	s_waitcnt lgkmcnt(0)
	v_and_b32_e32 v97, 0xffff0000, v140
	v_pk_fma_f32 v[94:95], v[94:95], 0.5, v[98:99] op_sel_hi:[1,0,1]
	v_pk_fma_f32 v[96:97], v[92:93], 0.5, v[96:97] op_sel_hi:[1,0,1]
	v_pk_mul_f32 v[98:99], v[94:95], v[94:95]
	v_cvt_pk_bf16_f32 v92, v96, v97
	v_cvt_pk_bf16_f32 v93, v94, v95
	v_lshlrev_b32_e32 v94, 16, v142
	v_and_b32_e32 v95, 0xffff0000, v142
	v_pk_fma_f32 v[96:97], v[96:97], v[96:97], v[98:99]
	v_pk_fma_f32 v[88:89], v[88:89], 0.5, v[94:95] op_sel_hi:[1,0,1]
	s_nop 0
	v_pk_fma_f32 v[96:97], v[88:89], v[88:89], v[96:97]
	v_cvt_pk_bf16_f32 v94, v88, v89
	v_lshlrev_b32_e32 v88, 16, v143
	v_and_b32_e32 v89, 0xffff0000, v143
	v_pk_fma_f32 v[88:89], v[90:91], 0.5, v[88:89] op_sel_hi:[1,0,1]
	s_nop 0
	v_pk_fma_f32 v[90:91], v[88:89], v[88:89], v[96:97]
	v_cvt_pk_bf16_f32 v95, v88, v89
	v_lshlrev_b32_e32 v88, 16, v136
	v_and_b32_e32 v89, 0xffff0000, v136
	v_pk_fma_f32 v[84:85], v[84:85], 0.5, v[88:89] op_sel_hi:[1,0,1]
	s_nop 0
	v_pk_fma_f32 v[88:89], v[84:85], v[84:85], v[90:91]
	v_lshlrev_b32_e32 v90, 16, v137
	v_and_b32_e32 v91, 0xffff0000, v137
	v_pk_fma_f32 v[86:87], v[86:87], 0.5, v[90:91] op_sel_hi:[1,0,1]
	v_lshlrev_b32_e32 v90, 16, v138
	v_and_b32_e32 v91, 0xffff0000, v138
	v_pk_fma_f32 v[88:89], v[86:87], v[86:87], v[88:89]
	v_pk_fma_f32 v[90:91], v[80:81], 0.5, v[90:91] op_sel_hi:[1,0,1]
	s_nop 0
	v_pk_fma_f32 v[80:81], v[90:91], v[90:91], v[88:89]
	v_lshlrev_b32_e32 v88, 16, v139
	v_and_b32_e32 v89, 0xffff0000, v139
	v_pk_fma_f32 v[88:89], v[82:83], 0.5, v[88:89] op_sel_hi:[1,0,1]
	s_nop 0
	v_pk_fma_f32 v[80:81], v[88:89], v[88:89], v[80:81]
	s_nop 0
	v_add_f32_e32 v83, v80, v81
	ds_bpermute_b32 v98, v193, v83
	v_lshl_add_u64 v[80:81], s[24:25], 0, v[180:181]
	v_lshl_add_u64 v[96:97], v[172:173], 1, v[80:81]
	global_store_dwordx4 v[96:97], v[92:95], off sc1
	v_cvt_pk_bf16_f32 v82, v84, v85
	s_waitcnt lgkmcnt(0)
	v_add_f32_e32 v80, v83, v98
	ds_bpermute_b32 v81, v112, v80
	v_cvt_pk_bf16_f32 v83, v86, v87
	v_cvt_pk_bf16_f32 v84, v90, v91
	v_cvt_pk_bf16_f32 v85, v88, v89
	global_store_dwordx4 v[96:97], v[82:85], off offset:256 sc1
	s_and_saveexec_b64 s[54:55], s[10:11]
	s_cbranch_execz .LBB0_619
	s_waitcnt lgkmcnt(0)
	v_add_f32_e32 v80, v80, v81
	ds_write_b32 v188, v80 offset:512
.LBB0_619:
	s_or_b64 exec, exec, s[54:55]
	v_lshlrev_b32_e32 v82, 16, v133
	v_and_b32_e32 v83, 0xffff0000, v133
	v_lshlrev_b32_e32 v80, 16, v132
	s_waitcnt lgkmcnt(0)
	v_and_b32_e32 v81, 0xffff0000, v132
	v_pk_fma_f32 v[78:79], v[78:79], 0.5, v[82:83] op_sel_hi:[1,0,1]
	v_pk_fma_f32 v[80:81], v[76:77], 0.5, v[80:81] op_sel_hi:[1,0,1]
	v_pk_mul_f32 v[82:83], v[78:79], v[78:79]
	v_cvt_pk_bf16_f32 v76, v80, v81
	v_cvt_pk_bf16_f32 v77, v78, v79
	v_lshlrev_b32_e32 v78, 16, v134
	v_and_b32_e32 v79, 0xffff0000, v134
	v_pk_fma_f32 v[80:81], v[80:81], v[80:81], v[82:83]
	v_pk_fma_f32 v[72:73], v[72:73], 0.5, v[78:79] op_sel_hi:[1,0,1]
	s_nop 0
	v_pk_fma_f32 v[80:81], v[72:73], v[72:73], v[80:81]
	v_cvt_pk_bf16_f32 v78, v72, v73
	v_lshlrev_b32_e32 v72, 16, v135
	v_and_b32_e32 v73, 0xffff0000, v135
	v_pk_fma_f32 v[72:73], v[74:75], 0.5, v[72:73] op_sel_hi:[1,0,1]
	s_nop 0
	v_pk_fma_f32 v[74:75], v[72:73], v[72:73], v[80:81]
	v_cvt_pk_bf16_f32 v79, v72, v73
	v_lshlrev_b32_e32 v72, 16, v128
	v_and_b32_e32 v73, 0xffff0000, v128
	v_pk_fma_f32 v[68:69], v[68:69], 0.5, v[72:73] op_sel_hi:[1,0,1]
	s_nop 0
	v_pk_fma_f32 v[72:73], v[68:69], v[68:69], v[74:75]
	v_lshlrev_b32_e32 v74, 16, v129
	v_and_b32_e32 v75, 0xffff0000, v129
	v_pk_fma_f32 v[70:71], v[70:71], 0.5, v[74:75] op_sel_hi:[1,0,1]
	v_lshlrev_b32_e32 v74, 16, v130
	v_and_b32_e32 v75, 0xffff0000, v130
	v_pk_fma_f32 v[72:73], v[70:71], v[70:71], v[72:73]
	v_pk_fma_f32 v[74:75], v[64:65], 0.5, v[74:75] op_sel_hi:[1,0,1]
	s_nop 0
	v_pk_fma_f32 v[64:65], v[74:75], v[74:75], v[72:73]
	v_lshlrev_b32_e32 v72, 16, v131
	v_and_b32_e32 v73, 0xffff0000, v131
	v_pk_fma_f32 v[72:73], v[66:67], 0.5, v[72:73] op_sel_hi:[1,0,1]
	s_nop 0
	v_pk_fma_f32 v[64:65], v[72:73], v[72:73], v[64:65]
	s_nop 0
	v_add_f32_e32 v67, v64, v65
	ds_bpermute_b32 v82, v193, v67
	v_lshl_add_u64 v[64:65], s[24:25], 0, v[178:179]
	v_lshl_add_u64 v[80:81], v[172:173], 1, v[64:65]
	global_store_dwordx4 v[80:81], v[76:79], off sc1
	v_cvt_pk_bf16_f32 v66, v68, v69
	s_waitcnt lgkmcnt(0)
	v_add_f32_e32 v64, v67, v82
	ds_bpermute_b32 v65, v112, v64
	v_cvt_pk_bf16_f32 v67, v70, v71
	v_cvt_pk_bf16_f32 v68, v74, v75
	v_cvt_pk_bf16_f32 v69, v72, v73
	global_store_dwordx4 v[80:81], v[66:69], off offset:256 sc1
	s_and_saveexec_b64 s[54:55], s[10:11]
	s_cbranch_execz .LBB0_621
	s_waitcnt lgkmcnt(0)
	v_add_f32_e32 v64, v64, v65
	ds_write_b32 v188, v64 offset:768
.LBB0_621:
	s_or_b64 exec, exec, s[54:55]
	s_waitcnt lgkmcnt(0)
	v_lshlrev_b64 v[64:65], 11, v[176:177]
	v_lshl_add_u64 v[102:103], v[64:65], 0, s[44:45]
	v_lshl_add_u64 v[66:67], v[174:175], 0, v[102:103]
	global_load_dwordx4 v[94:97], v[66:67], off
	global_load_dwordx4 v[98:101], v[66:67], off offset:256
	v_lshl_add_u64 v[92:93], v[64:65], 0, s[46:47]
	v_lshl_add_u64 v[90:91], v[64:65], 0, s[48:49]
	v_lshl_add_u64 v[88:89], v[64:65], 0, s[50:51]
	v_lshl_add_u64 v[64:65], v[174:175], 0, v[92:93]
	v_lshl_add_u64 v[66:67], v[174:175], 0, v[90:91]
	v_lshl_add_u64 v[104:105], v[174:175], 0, v[88:89]
	global_load_dwordx4 v[84:87], v[64:65], off
	global_load_dwordx4 v[80:83], v[64:65], off offset:256
	global_load_dwordx4 v[76:79], v[66:67], off
	global_load_dwordx4 v[72:75], v[66:67], off offset:256
	global_load_dwordx4 v[68:71], v[104:105], off
	s_nop 0
	global_load_dwordx4 v[64:67], v[104:105], off offset:256
	s_waitcnt vmcnt(7)
	v_lshlrev_b32_e32 v104, 16, v94
	v_and_b32_e32 v105, 0xffff0000, v94
	v_lshlrev_b32_e32 v94, 16, v95
	v_and_b32_e32 v95, 0xffff0000, v95
	v_lshlrev_b32_e32 v106, 16, v96
	v_and_b32_e32 v107, 0xffff0000, v96
	v_lshlrev_b32_e32 v96, 16, v97
	v_and_b32_e32 v97, 0xffff0000, v97
	s_waitcnt vmcnt(6)
	v_lshlrev_b32_e32 v108, 16, v98
	v_and_b32_e32 v109, 0xffff0000, v98
	v_lshlrev_b32_e32 v98, 16, v99
	v_and_b32_e32 v99, 0xffff0000, v99
	v_lshlrev_b32_e32 v110, 16, v100
	v_and_b32_e32 v111, 0xffff0000, v100
	v_pk_fma_f32 v[62:63], v[62:63], 0.5, v[94:95] op_sel_hi:[1,0,1]
	v_pk_fma_f32 v[60:61], v[60:61], 0.5, v[104:105] op_sel_hi:[1,0,1]
	v_pk_fma_f32 v[58:59], v[58:59], 0.5, v[96:97] op_sel_hi:[1,0,1]
	v_pk_fma_f32 v[96:97], v[54:55], 0.5, v[98:99] op_sel_hi:[1,0,1]
	v_pk_fma_f32 v[98:99], v[48:49], 0.5, v[110:111] op_sel_hi:[1,0,1]
	v_pk_mul_f32 v[48:49], v[62:63], v[62:63]
	v_pk_fma_f32 v[56:57], v[56:57], 0.5, v[106:107] op_sel_hi:[1,0,1]
	v_pk_fma_f32 v[48:49], v[60:61], v[60:61], v[48:49]
	v_pk_fma_f32 v[94:95], v[52:53], 0.5, v[108:109] op_sel_hi:[1,0,1]
	v_pk_fma_f32 v[48:49], v[56:57], v[56:57], v[48:49]
	v_lshlrev_b32_e32 v100, 16, v101
	v_pk_fma_f32 v[48:49], v[58:59], v[58:59], v[48:49]
	v_and_b32_e32 v101, 0xffff0000, v101
	v_pk_fma_f32 v[48:49], v[94:95], v[94:95], v[48:49]
	v_cvt_pk_bf16_f32 v52, v60, v61
	v_cvt_pk_bf16_f32 v53, v62, v63
	v_cvt_pk_bf16_f32 v54, v56, v57
	v_pk_fma_f32 v[56:57], v[50:51], 0.5, v[100:101] op_sel_hi:[1,0,1]
	v_pk_fma_f32 v[48:49], v[96:97], v[96:97], v[48:49]
	v_cvt_pk_bf16_f32 v55, v58, v59
	s_nop 0
	v_pk_fma_f32 v[48:49], v[98:99], v[98:99], v[48:49]
	s_nop 0
	v_pk_fma_f32 v[48:49], v[56:57], v[56:57], v[48:49]
	s_nop 0
	v_add_f32_e32 v51, v48, v49
	ds_bpermute_b32 v60, v193, v51
	v_lshl_add_u64 v[48:49], s[24:25], 0, v[102:103]
	v_lshl_add_u64 v[58:59], v[172:173], 1, v[48:49]
	global_store_dwordx4 v[58:59], v[52:55], off sc1
	v_cvt_pk_bf16_f32 v50, v94, v95
	s_waitcnt lgkmcnt(0)
	v_add_f32_e32 v48, v51, v60
	ds_bpermute_b32 v49, v112, v48
	v_cvt_pk_bf16_f32 v51, v96, v97
	v_cvt_pk_bf16_f32 v52, v98, v99
	v_cvt_pk_bf16_f32 v53, v56, v57
	global_store_dwordx4 v[58:59], v[50:53], off offset:256 sc1
	s_and_saveexec_b64 s[54:55], s[10:11]
	s_cbranch_execz .LBB0_623
	s_waitcnt lgkmcnt(0)
	v_add_f32_e32 v48, v48, v49
	ds_write_b32 v188, v48 offset:2048
.LBB0_623:
	s_or_b64 exec, exec, s[54:55]
	s_waitcnt vmcnt(7)
	v_lshlrev_b32_e32 v50, 16, v85
	v_and_b32_e32 v51, 0xffff0000, v85
	v_lshlrev_b32_e32 v48, 16, v84
	s_waitcnt lgkmcnt(0)
	v_and_b32_e32 v49, 0xffff0000, v84
	v_pk_fma_f32 v[46:47], v[46:47], 0.5, v[50:51] op_sel_hi:[1,0,1]
	v_pk_fma_f32 v[48:49], v[44:45], 0.5, v[48:49] op_sel_hi:[1,0,1]
	v_pk_mul_f32 v[50:51], v[46:47], v[46:47]
	v_cvt_pk_bf16_f32 v44, v48, v49
	v_cvt_pk_bf16_f32 v45, v46, v47
	v_lshlrev_b32_e32 v46, 16, v86
	v_and_b32_e32 v47, 0xffff0000, v86
	v_pk_fma_f32 v[48:49], v[48:49], v[48:49], v[50:51]
	v_pk_fma_f32 v[40:41], v[40:41], 0.5, v[46:47] op_sel_hi:[1,0,1]
	s_nop 0
	v_pk_fma_f32 v[48:49], v[40:41], v[40:41], v[48:49]
	v_cvt_pk_bf16_f32 v46, v40, v41
	v_lshlrev_b32_e32 v40, 16, v87
	v_and_b32_e32 v41, 0xffff0000, v87
	v_pk_fma_f32 v[40:41], v[42:43], 0.5, v[40:41] op_sel_hi:[1,0,1]
	s_nop 0
	v_pk_fma_f32 v[42:43], v[40:41], v[40:41], v[48:49]
	v_cvt_pk_bf16_f32 v47, v40, v41
	s_waitcnt vmcnt(6)
	v_lshlrev_b32_e32 v40, 16, v80
	v_and_b32_e32 v41, 0xffff0000, v80
	v_pk_fma_f32 v[36:37], v[36:37], 0.5, v[40:41] op_sel_hi:[1,0,1]
	s_nop 0
	v_pk_fma_f32 v[40:41], v[36:37], v[36:37], v[42:43]
	v_lshlrev_b32_e32 v42, 16, v81
	v_and_b32_e32 v43, 0xffff0000, v81
	v_pk_fma_f32 v[38:39], v[38:39], 0.5, v[42:43] op_sel_hi:[1,0,1]
	v_lshlrev_b32_e32 v42, 16, v82
	v_and_b32_e32 v43, 0xffff0000, v82
	v_pk_fma_f32 v[40:41], v[38:39], v[38:39], v[40:41]
	v_pk_fma_f32 v[42:43], v[32:33], 0.5, v[42:43] op_sel_hi:[1,0,1]
	s_nop 0
	v_pk_fma_f32 v[32:33], v[42:43], v[42:43], v[40:41]
	v_lshlrev_b32_e32 v40, 16, v83
	v_and_b32_e32 v41, 0xffff0000, v83
	v_pk_fma_f32 v[40:41], v[34:35], 0.5, v[40:41] op_sel_hi:[1,0,1]
	s_nop 0
	v_pk_fma_f32 v[32:33], v[40:41], v[40:41], v[32:33]
	s_nop 0
	v_add_f32_e32 v35, v32, v33
	ds_bpermute_b32 v50, v193, v35
	v_lshl_add_u64 v[32:33], s[24:25], 0, v[92:93]
	v_lshl_add_u64 v[48:49], v[172:173], 1, v[32:33]
	global_store_dwordx4 v[48:49], v[44:47], off sc1
	v_cvt_pk_bf16_f32 v34, v36, v37
	s_waitcnt lgkmcnt(0)
	v_add_f32_e32 v32, v35, v50
	ds_bpermute_b32 v33, v112, v32
	v_cvt_pk_bf16_f32 v35, v38, v39
	v_cvt_pk_bf16_f32 v36, v42, v43
	v_cvt_pk_bf16_f32 v37, v40, v41
	global_store_dwordx4 v[48:49], v[34:37], off offset:256 sc1
	s_and_saveexec_b64 s[54:55], s[10:11]
	s_cbranch_execz .LBB0_625
	s_waitcnt lgkmcnt(0)
	v_add_f32_e32 v32, v32, v33
	ds_write_b32 v188, v32 offset:2304
.LBB0_625:
	s_or_b64 exec, exec, s[54:55]
	s_waitcnt vmcnt(7)
	v_lshlrev_b32_e32 v34, 16, v77
	v_and_b32_e32 v35, 0xffff0000, v77
	v_lshlrev_b32_e32 v32, 16, v76
	s_waitcnt lgkmcnt(0)
	v_and_b32_e32 v33, 0xffff0000, v76
	v_pk_fma_f32 v[30:31], v[30:31], 0.5, v[34:35] op_sel_hi:[1,0,1]
	v_pk_fma_f32 v[32:33], v[28:29], 0.5, v[32:33] op_sel_hi:[1,0,1]
	v_pk_mul_f32 v[34:35], v[30:31], v[30:31]
	v_cvt_pk_bf16_f32 v28, v32, v33
	v_cvt_pk_bf16_f32 v29, v30, v31
	v_lshlrev_b32_e32 v30, 16, v78
	v_and_b32_e32 v31, 0xffff0000, v78
	v_pk_fma_f32 v[32:33], v[32:33], v[32:33], v[34:35]
	v_pk_fma_f32 v[24:25], v[24:25], 0.5, v[30:31] op_sel_hi:[1,0,1]
	s_nop 0
	v_pk_fma_f32 v[32:33], v[24:25], v[24:25], v[32:33]
	v_cvt_pk_bf16_f32 v30, v24, v25
	v_lshlrev_b32_e32 v24, 16, v79
	v_and_b32_e32 v25, 0xffff0000, v79
	v_pk_fma_f32 v[24:25], v[26:27], 0.5, v[24:25] op_sel_hi:[1,0,1]
	s_nop 0
	v_pk_fma_f32 v[26:27], v[24:25], v[24:25], v[32:33]
	v_cvt_pk_bf16_f32 v31, v24, v25
	s_waitcnt vmcnt(6)
	v_lshlrev_b32_e32 v24, 16, v72
	v_and_b32_e32 v25, 0xffff0000, v72
	v_pk_fma_f32 v[20:21], v[20:21], 0.5, v[24:25] op_sel_hi:[1,0,1]
	s_nop 0
	v_pk_fma_f32 v[24:25], v[20:21], v[20:21], v[26:27]
	v_lshlrev_b32_e32 v26, 16, v73
	v_and_b32_e32 v27, 0xffff0000, v73
	v_pk_fma_f32 v[22:23], v[22:23], 0.5, v[26:27] op_sel_hi:[1,0,1]
	v_lshlrev_b32_e32 v26, 16, v74
	v_and_b32_e32 v27, 0xffff0000, v74
	v_pk_fma_f32 v[24:25], v[22:23], v[22:23], v[24:25]
	v_pk_fma_f32 v[26:27], v[16:17], 0.5, v[26:27] op_sel_hi:[1,0,1]
	s_nop 0
	v_pk_fma_f32 v[16:17], v[26:27], v[26:27], v[24:25]
	v_lshlrev_b32_e32 v24, 16, v75
	v_and_b32_e32 v25, 0xffff0000, v75
	v_pk_fma_f32 v[24:25], v[18:19], 0.5, v[24:25] op_sel_hi:[1,0,1]
	s_nop 0
	v_pk_fma_f32 v[16:17], v[24:25], v[24:25], v[16:17]
	s_nop 0
	v_add_f32_e32 v19, v16, v17
	ds_bpermute_b32 v34, v193, v19
	v_lshl_add_u64 v[16:17], s[24:25], 0, v[90:91]
	v_lshl_add_u64 v[32:33], v[172:173], 1, v[16:17]
	global_store_dwordx4 v[32:33], v[28:31], off sc1
	v_cvt_pk_bf16_f32 v18, v20, v21
	s_waitcnt lgkmcnt(0)
	v_add_f32_e32 v16, v19, v34
	ds_bpermute_b32 v17, v112, v16
	v_cvt_pk_bf16_f32 v19, v22, v23
	v_cvt_pk_bf16_f32 v20, v26, v27
	v_cvt_pk_bf16_f32 v21, v24, v25
	global_store_dwordx4 v[32:33], v[18:21], off offset:256 sc1
	s_and_saveexec_b64 s[54:55], s[10:11]
	s_cbranch_execz .LBB0_627
	s_waitcnt lgkmcnt(0)
	v_add_f32_e32 v16, v16, v17
	ds_write_b32 v188, v16 offset:2560
.LBB0_627:
	s_or_b64 exec, exec, s[54:55]
	s_waitcnt vmcnt(7)
	v_lshlrev_b32_e32 v18, 16, v69
	v_and_b32_e32 v19, 0xffff0000, v69
	v_lshlrev_b32_e32 v16, 16, v68
	s_waitcnt lgkmcnt(0)
	v_and_b32_e32 v17, 0xffff0000, v68
	v_pk_fma_f32 v[14:15], v[14:15], 0.5, v[18:19] op_sel_hi:[1,0,1]
	v_pk_fma_f32 v[16:17], v[12:13], 0.5, v[16:17] op_sel_hi:[1,0,1]
	v_pk_mul_f32 v[18:19], v[14:15], v[14:15]
	v_cvt_pk_bf16_f32 v12, v16, v17
	v_cvt_pk_bf16_f32 v13, v14, v15
	v_lshlrev_b32_e32 v14, 16, v70
	v_and_b32_e32 v15, 0xffff0000, v70
	v_pk_fma_f32 v[16:17], v[16:17], v[16:17], v[18:19]
	v_pk_fma_f32 v[8:9], v[8:9], 0.5, v[14:15] op_sel_hi:[1,0,1]
	s_nop 0
	v_pk_fma_f32 v[16:17], v[8:9], v[8:9], v[16:17]
	v_cvt_pk_bf16_f32 v14, v8, v9
	v_lshlrev_b32_e32 v8, 16, v71
	v_and_b32_e32 v9, 0xffff0000, v71
	v_pk_fma_f32 v[8:9], v[10:11], 0.5, v[8:9] op_sel_hi:[1,0,1]
	s_nop 0
	v_pk_fma_f32 v[10:11], v[8:9], v[8:9], v[16:17]
	v_cvt_pk_bf16_f32 v15, v8, v9
	s_waitcnt vmcnt(6)
	v_lshlrev_b32_e32 v8, 16, v64
	v_and_b32_e32 v9, 0xffff0000, v64
	v_pk_fma_f32 v[4:5], v[4:5], 0.5, v[8:9] op_sel_hi:[1,0,1]
	s_nop 0
	v_pk_fma_f32 v[8:9], v[4:5], v[4:5], v[10:11]
	v_lshlrev_b32_e32 v10, 16, v65
	v_and_b32_e32 v11, 0xffff0000, v65
	v_pk_fma_f32 v[6:7], v[6:7], 0.5, v[10:11] op_sel_hi:[1,0,1]
	v_lshlrev_b32_e32 v10, 16, v66
	v_and_b32_e32 v11, 0xffff0000, v66
	v_pk_fma_f32 v[8:9], v[6:7], v[6:7], v[8:9]
	v_pk_fma_f32 v[10:11], v[0:1], 0.5, v[10:11] op_sel_hi:[1,0,1]
	s_nop 0
	v_pk_fma_f32 v[0:1], v[10:11], v[10:11], v[8:9]
	v_lshlrev_b32_e32 v8, 16, v67
	v_and_b32_e32 v9, 0xffff0000, v67
	v_pk_fma_f32 v[8:9], v[2:3], 0.5, v[8:9] op_sel_hi:[1,0,1]
	s_nop 0
	v_pk_fma_f32 v[0:1], v[8:9], v[8:9], v[0:1]
	s_nop 0
	v_add_f32_e32 v3, v0, v1
	ds_bpermute_b32 v18, v193, v3
	v_lshl_add_u64 v[0:1], s[24:25], 0, v[88:89]
	v_lshl_add_u64 v[16:17], v[172:173], 1, v[0:1]
	global_store_dwordx4 v[16:17], v[12:15], off sc1
	v_cvt_pk_bf16_f32 v2, v4, v5
	s_waitcnt lgkmcnt(0)
	v_add_f32_e32 v0, v3, v18
	ds_bpermute_b32 v1, v112, v0
	v_cvt_pk_bf16_f32 v3, v6, v7
	v_cvt_pk_bf16_f32 v4, v10, v11
	v_cvt_pk_bf16_f32 v5, v8, v9
	global_store_dwordx4 v[16:17], v[2:5], off offset:256 sc1
	s_and_saveexec_b64 s[54:55], s[10:11]
	s_cbranch_execz .LBB0_629
	s_waitcnt lgkmcnt(0)
	v_add_f32_e32 v0, v0, v1
	ds_write_b32 v188, v0 offset:2816
.LBB0_629:
	s_or_b64 exec, exec, s[54:55]
	s_waitcnt lgkmcnt(0)
	s_barrier
	s_and_saveexec_b64 s[54:55], s[12:13]
	s_cbranch_execz .LBB0_631
	s_waitcnt lgkmcnt(0)
	ds_read_b128 v[0:3], v192
	v_or_b32_e32 v4, s21, v157
	v_ashrrev_i32_e32 v5, 31, v4
	s_ashr_i32 s21, s20, 31
	s_waitcnt lgkmcnt(0)
	v_mov_b32_e32 v6, v1
	v_mov_b32_e32 v7, v2
	v_mov_b32_e32 v1, v3
	v_pk_add_f32 v[0:1], v[6:7], v[0:1]
	s_nop 0
	v_add_f32_e32 v2, v0, v1
	v_lshl_add_u64 v[0:1], v[4:5], 4, s[26:27]
	v_lshl_add_u64 v[0:1], s[20:21], 2, v[0:1]
	global_store_dword v[0:1], v2, off sc1

.LBB0_879:
	v_add_u32_e32 v144, 0x21000, v155
	ds_read_b128 v[162:165], v144
	v_add_u32_e32 v144, 0x21100, v155
	ds_read_b128 v[166:169], v144
	s_waitcnt lgkmcnt(0)
	v_mov_b32_e32 v144, v163
	v_mov_b32_e32 v145, v164
	v_mov_b32_e32 v163, v165
	v_pk_add_f32 v[144:145], v[144:145], v[162:163]
	s_nop 0
	v_add_f32_e32 v144, v144, v145
	v_fmamk_f32 v144, v144, 0x3a800000, v160
	v_rsq_f32_e32 v170, v144
	v_mov_b32_e32 v144, v167
	v_mov_b32_e32 v145, v168
	v_mov_b32_e32 v167, v169
	v_pk_add_f32 v[144:145], v[144:145], v[166:167]
	v_pk_mul_f32 v[124:125], v[124:125], v[170:171] op_sel_hi:[1,0]
	v_add_f32_e32 v144, v144, v145
	v_add_u32_e32 v145, 0x21200, v155
	ds_read_b128 v[162:165], v145
	v_fmamk_f32 v144, v144, 0x3a800000, v160
	v_rsq_f32_e32 v172, v144
	v_add_u32_e32 v144, 0x21300, v155
	ds_read_b128 v[166:169], v144
	s_waitcnt lgkmcnt(0)
	v_mov_b32_e32 v144, v163
	v_mov_b32_e32 v145, v164
	v_mov_b32_e32 v163, v165
	v_pk_add_f32 v[144:145], v[144:145], v[162:163]
	v_pk_mul_f32 v[126:127], v[126:127], v[170:171] op_sel_hi:[1,0]
	v_add_f32_e32 v144, v144, v145
	v_fmamk_f32 v144, v144, 0x3a800000, v160
	v_rsq_f32_e32 v174, v144
	v_mov_b32_e32 v144, v167
	v_mov_b32_e32 v145, v168
	v_mov_b32_e32 v167, v169
	v_pk_add_f32 v[144:145], v[144:145], v[166:167]
	v_pk_mul_f32 v[120:121], v[120:121], v[170:171] op_sel_hi:[1,0]
	v_add_f32_e32 v144, v144, v145
	v_add_u32_e32 v145, 0x21800, v155
	ds_read_b128 v[162:165], v145
	v_fmamk_f32 v144, v144, 0x3a800000, v160
	v_rsq_f32_e32 v152, v144
	v_add_u32_e32 v144, 0x21900, v155
	ds_read_b128 v[166:169], v144
	s_waitcnt lgkmcnt(0)
	v_mov_b32_e32 v144, v163
	v_mov_b32_e32 v145, v164
	v_mov_b32_e32 v163, v165
	v_pk_add_f32 v[144:145], v[144:145], v[162:163]
	v_pk_mul_f32 v[116:117], v[116:117], v[170:171] op_sel_hi:[1,0]
	v_add_f32_e32 v144, v144, v145
	v_fmamk_f32 v144, v144, 0x3a800000, v160
	v_rsq_f32_e32 v150, v144
	v_mov_b32_e32 v144, v167
	v_mov_b32_e32 v145, v168
	v_mov_b32_e32 v167, v169
	v_pk_add_f32 v[144:145], v[144:145], v[166:167]
	v_pk_mul_f32 v[118:119], v[118:119], v[170:171] op_sel_hi:[1,0]
	v_add_f32_e32 v144, v144, v145
	v_add_u32_e32 v145, 0x21a00, v155
	ds_read_b128 v[162:165], v145
	v_fmamk_f32 v144, v144, 0x3a800000, v160
	v_rsq_f32_e32 v148, v144
	v_add_u32_e32 v144, 0x21b00, v155
	ds_read_b128 v[166:169], v144
	s_waitcnt lgkmcnt(0)
	v_mov_b32_e32 v144, v163
	v_mov_b32_e32 v145, v164
	v_mov_b32_e32 v163, v165
	v_pk_add_f32 v[144:145], v[144:145], v[162:163]
	v_add_u32_e32 v162, s47, v147
	v_lshl_or_b32 v164, s79, 8, v153
	v_ashrrev_i32_e32 v165, 31, v164
	v_ashrrev_i32_e32 v163, 31, v162
	v_cvt_pk_bf16_f32 v124, v124, v125
	v_cvt_pk_bf16_f32 v125, v126, v127
	v_cvt_pk_bf16_f32 v126, v120, v121
	v_pk_mul_f32 v[120:121], v[122:123], v[170:171] op_sel_hi:[1,0]
	v_lshl_add_u64 v[164:165], v[164:165], 1, s[16:17]
	v_cvt_pk_bf16_f32 v127, v120, v121
	v_lshlrev_b64 v[120:121], 11, v[162:163]
	v_lshl_add_u64 v[120:121], v[164:165], 0, v[120:121]
	v_pk_mul_f32 v[108:109], v[108:109], v[170:171] op_sel_hi:[1,0]
	global_store_dwordx4 v[120:121], v[124:127], off sc1
	v_cvt_pk_bf16_f32 v116, v116, v117
	v_cvt_pk_bf16_f32 v117, v118, v119
	v_cvt_pk_bf16_f32 v118, v108, v109
	v_pk_mul_f32 v[108:109], v[110:111], v[170:171] op_sel_hi:[1,0]
	v_pk_mul_f32 v[110:111], v[114:115], v[172:173] op_sel_hi:[1,0]
	v_cvt_pk_bf16_f32 v119, v108, v109
	global_store_dwordx4 v[120:121], v[116:119], off offset:256 sc1
	v_pk_mul_f32 v[108:109], v[112:113], v[172:173] op_sel_hi:[1,0]
	v_pk_mul_f32 v[104:105], v[104:105], v[172:173] op_sel_hi:[1,0]
	v_or_b32_e32 v116, 16, v162
	v_ashrrev_i32_e32 v117, 31, v116
	v_cvt_pk_bf16_f32 v108, v108, v109
	v_cvt_pk_bf16_f32 v109, v110, v111
	v_cvt_pk_bf16_f32 v110, v104, v105
	v_pk_mul_f32 v[104:105], v[106:107], v[172:173] op_sel_hi:[1,0]
	v_pk_mul_f32 v[100:101], v[100:101], v[172:173] op_sel_hi:[1,0]
	v_cvt_pk_bf16_f32 v111, v104, v105
	v_lshlrev_b64 v[104:105], 11, v[116:117]
	v_lshl_add_u64 v[104:105], v[164:165], 0, v[104:105]
	v_pk_mul_f32 v[102:103], v[102:103], v[172:173] op_sel_hi:[1,0]
	v_pk_mul_f32 v[92:93], v[92:93], v[172:173] op_sel_hi:[1,0]
	global_store_dwordx4 v[104:105], v[108:111], off sc1
	v_cvt_pk_bf16_f32 v100, v100, v101
	v_cvt_pk_bf16_f32 v101, v102, v103
	v_cvt_pk_bf16_f32 v102, v92, v93
	v_pk_mul_f32 v[92:93], v[94:95], v[172:173] op_sel_hi:[1,0]
	v_pk_mul_f32 v[94:95], v[98:99], v[174:175] op_sel_hi:[1,0]
	v_cvt_pk_bf16_f32 v103, v92, v93
	global_store_dwordx4 v[104:105], v[100:103], off offset:256 sc1
	v_pk_mul_f32 v[92:93], v[96:97], v[174:175] op_sel_hi:[1,0]
	v_pk_mul_f32 v[88:89], v[88:89], v[174:175] op_sel_hi:[1,0]
	v_or_b32_e32 v100, 32, v162
	v_ashrrev_i32_e32 v101, 31, v100
	v_cvt_pk_bf16_f32 v92, v92, v93
	v_cvt_pk_bf16_f32 v93, v94, v95
	v_cvt_pk_bf16_f32 v94, v88, v89
	v_pk_mul_f32 v[88:89], v[90:91], v[174:175] op_sel_hi:[1,0]
	v_pk_mul_f32 v[84:85], v[84:85], v[174:175] op_sel_hi:[1,0]
	v_cvt_pk_bf16_f32 v95, v88, v89
	v_lshlrev_b64 v[88:89], 11, v[100:101]
	v_lshl_add_u64 v[88:89], v[164:165], 0, v[88:89]
	v_pk_mul_f32 v[86:87], v[86:87], v[174:175] op_sel_hi:[1,0]
	v_pk_mul_f32 v[76:77], v[76:77], v[174:175] op_sel_hi:[1,0]
	global_store_dwordx4 v[88:89], v[92:95], off sc1
	v_cvt_pk_bf16_f32 v84, v84, v85
	v_cvt_pk_bf16_f32 v85, v86, v87
	v_cvt_pk_bf16_f32 v86, v76, v77
	v_pk_mul_f32 v[76:77], v[78:79], v[174:175] op_sel_hi:[1,0]
	v_pk_mul_f32 v[78:79], v[82:83], v[152:153] op_sel_hi:[1,0]
	v_cvt_pk_bf16_f32 v87, v76, v77
	global_store_dwordx4 v[88:89], v[84:87], off offset:256 sc1
	v_pk_mul_f32 v[76:77], v[80:81], v[152:153] op_sel_hi:[1,0]
	v_pk_mul_f32 v[72:73], v[72:73], v[152:153] op_sel_hi:[1,0]
	v_or_b32_e32 v84, 48, v162
	v_ashrrev_i32_e32 v85, 31, v84
	v_cvt_pk_bf16_f32 v76, v76, v77
	v_cvt_pk_bf16_f32 v77, v78, v79
	v_cvt_pk_bf16_f32 v78, v72, v73
	v_pk_mul_f32 v[72:73], v[74:75], v[152:153] op_sel_hi:[1,0]
	v_pk_mul_f32 v[68:69], v[68:69], v[152:153] op_sel_hi:[1,0]
	v_cvt_pk_bf16_f32 v79, v72, v73
	v_lshlrev_b64 v[72:73], 11, v[84:85]
	v_lshl_add_u64 v[72:73], v[164:165], 0, v[72:73]
	v_pk_mul_f32 v[70:71], v[70:71], v[152:153] op_sel_hi:[1,0]
	v_pk_mul_f32 v[64:65], v[64:65], v[152:153] op_sel_hi:[1,0]
	v_pk_mul_f32 v[60:61], v[60:61], v[150:151] op_sel_hi:[1,0]
	v_pk_mul_f32 v[62:63], v[62:63], v[150:151] op_sel_hi:[1,0]
	v_pk_mul_f32 v[56:57], v[56:57], v[150:151] op_sel_hi:[1,0]
	global_store_dwordx4 v[72:73], v[76:79], off sc1
	v_cvt_pk_bf16_f32 v68, v68, v69
	v_cvt_pk_bf16_f32 v69, v70, v71
	v_cvt_pk_bf16_f32 v70, v64, v65
	v_pk_mul_f32 v[64:65], v[66:67], v[152:153] op_sel_hi:[1,0]
	v_add_f32_e32 v144, v144, v145
	v_cvt_pk_bf16_f32 v71, v64, v65
	global_store_dwordx4 v[72:73], v[68:71], off offset:256 sc1
	v_cvt_pk_bf16_f32 v60, v60, v61
	v_cvt_pk_bf16_f32 v61, v62, v63
	v_cvt_pk_bf16_f32 v62, v56, v57
	v_pk_mul_f32 v[56:57], v[58:59], v[150:151] op_sel_hi:[1,0]
	v_add_co_u32_e32 v58, vcc, s75, v120
	v_pk_mul_f32 v[52:53], v[52:53], v[150:151] op_sel_hi:[1,0]
	s_nop 0
	v_addc_co_u32_e32 v59, vcc, 0, v121, vcc
	v_pk_mul_f32 v[54:55], v[54:55], v[150:151] op_sel_hi:[1,0]
	v_pk_mul_f32 v[44:45], v[44:45], v[150:151] op_sel_hi:[1,0]
	v_fmamk_f32 v144, v144, 0x3a800000, v160
	v_cvt_pk_bf16_f32 v63, v56, v57
	global_store_dwordx4 v[58:59], v[60:63], off sc1
	v_cvt_pk_bf16_f32 v52, v52, v53
	v_cvt_pk_bf16_f32 v53, v54, v55
	v_cvt_pk_bf16_f32 v54, v44, v45
	v_pk_mul_f32 v[44:45], v[46:47], v[150:151] op_sel_hi:[1,0]
	v_rsq_f32_e32 v146, v144
	v_mov_b32_e32 v144, v167
	v_mov_b32_e32 v145, v168
	v_mov_b32_e32 v167, v169
	v_lshl_add_u64 v[56:57], v[120:121], 0, s[12:13]
	v_cvt_pk_bf16_f32 v55, v44, v45
	v_pk_mul_f32 v[44:45], v[48:49], v[148:149] op_sel_hi:[1,0]
	v_pk_mul_f32 v[46:47], v[50:51], v[148:149] op_sel_hi:[1,0]
	v_pk_mul_f32 v[40:41], v[40:41], v[148:149] op_sel_hi:[1,0]
	v_pk_add_f32 v[144:145], v[144:145], v[166:167]
	global_store_dwordx4 v[56:57], v[52:55], off offset:256 sc1
	v_cvt_pk_bf16_f32 v44, v44, v45
	v_cvt_pk_bf16_f32 v45, v46, v47
	v_cvt_pk_bf16_f32 v46, v40, v41
	v_pk_mul_f32 v[40:41], v[42:43], v[148:149] op_sel_hi:[1,0]
	v_add_co_u32_e32 v42, vcc, s76, v120
	v_add_f32_e32 v144, v144, v145
	s_nop 0
	v_addc_co_u32_e32 v43, vcc, 0, v121, vcc
	v_pk_mul_f32 v[36:37], v[36:37], v[148:149] op_sel_hi:[1,0]
	v_pk_mul_f32 v[38:39], v[38:39], v[148:149] op_sel_hi:[1,0]
	v_pk_mul_f32 v[28:29], v[28:29], v[148:149] op_sel_hi:[1,0]
	v_fmamk_f32 v144, v144, 0x3a800000, v160
	v_cvt_pk_bf16_f32 v47, v40, v41
	global_store_dwordx4 v[42:43], v[44:47], off sc1
	v_cvt_pk_bf16_f32 v36, v36, v37
	v_cvt_pk_bf16_f32 v37, v38, v39
	v_cvt_pk_bf16_f32 v38, v28, v29
	v_pk_mul_f32 v[28:29], v[30:31], v[148:149] op_sel_hi:[1,0]
	v_rsq_f32_e32 v144, v144
	v_lshl_add_u64 v[40:41], v[120:121], 0, s[28:29]
	v_cvt_pk_bf16_f32 v39, v28, v29
	v_pk_mul_f32 v[28:29], v[32:33], v[146:147] op_sel_hi:[1,0]
	v_pk_mul_f32 v[30:31], v[34:35], v[146:147] op_sel_hi:[1,0]
	v_pk_mul_f32 v[24:25], v[24:25], v[146:147] op_sel_hi:[1,0]
	global_store_dwordx4 v[40:41], v[36:39], off offset:256 sc1
	v_cvt_pk_bf16_f32 v28, v28, v29
	v_cvt_pk_bf16_f32 v29, v30, v31
	v_cvt_pk_bf16_f32 v30, v24, v25
	v_pk_mul_f32 v[24:25], v[26:27], v[146:147] op_sel_hi:[1,0]
	v_add_co_u32_e32 v26, vcc, s77, v120
	v_pk_mul_f32 v[20:21], v[20:21], v[146:147] op_sel_hi:[1,0]
	s_nop 0
	v_addc_co_u32_e32 v27, vcc, 0, v121, vcc
	v_pk_mul_f32 v[22:23], v[22:23], v[146:147] op_sel_hi:[1,0]
	v_pk_mul_f32 v[12:13], v[12:13], v[146:147] op_sel_hi:[1,0]
	v_cvt_pk_bf16_f32 v31, v24, v25
	global_store_dwordx4 v[26:27], v[28:31], off sc1
	v_cvt_pk_bf16_f32 v20, v20, v21
	v_cvt_pk_bf16_f32 v21, v22, v23
	v_cvt_pk_bf16_f32 v22, v12, v13
	v_pk_mul_f32 v[12:13], v[14:15], v[146:147] op_sel_hi:[1,0]
	v_lshl_add_u64 v[24:25], v[120:121], 0, s[30:31]
	v_cvt_pk_bf16_f32 v23, v12, v13
	v_pk_mul_f32 v[12:13], v[16:17], v[144:145] op_sel_hi:[1,0]
	v_pk_mul_f32 v[14:15], v[18:19], v[144:145] op_sel_hi:[1,0]
	v_pk_mul_f32 v[8:9], v[8:9], v[144:145] op_sel_hi:[1,0]
	global_store_dwordx4 v[24:25], v[20:23], off offset:256 sc1
	v_cvt_pk_bf16_f32 v12, v12, v13
	v_cvt_pk_bf16_f32 v13, v14, v15
	v_cvt_pk_bf16_f32 v14, v8, v9
	v_pk_mul_f32 v[8:9], v[10:11], v[144:145] op_sel_hi:[1,0]
	v_add_co_u32_e32 v10, vcc, s78, v120
	v_cvt_pk_bf16_f32 v15, v8, v9
	v_lshl_add_u64 v[8:9], v[120:121], 0, s[44:45]
	s_nop 0
	v_addc_co_u32_e32 v11, vcc, 0, v121, vcc
	v_pk_mul_f32 v[4:5], v[4:5], v[144:145] op_sel_hi:[1,0]
	v_pk_mul_f32 v[6:7], v[6:7], v[144:145] op_sel_hi:[1,0]
	v_pk_mul_f32 v[0:1], v[0:1], v[144:145] op_sel_hi:[1,0]
	s_andn2_b64 vcc, exec, s[10:11]
	s_mov_b64 s[10:11], -1
	global_store_dwordx4 v[10:11], v[12:15], off sc1
	v_cvt_pk_bf16_f32 v4, v4, v5
	v_cvt_pk_bf16_f32 v5, v6, v7
	v_cvt_pk_bf16_f32 v6, v0, v1
	v_pk_mul_f32 v[0:1], v[2:3], v[144:145] op_sel_hi:[1,0]
	s_nop 0
	v_cvt_pk_bf16_f32 v7, v0, v1
	global_store_dwordx4 v[8:9], v[4:7], off offset:256 sc1
	s_cbranch_vccnz .LBB0_866
	s_andn2_b64 vcc, exec, s[14:15]
	s_cbranch_vccnz .LBB0_865
	s_barrier
	s_branch .LBB0_865

.LBB0_1014:
	s_lshl_b32 s15, s56, 8
	v_lshl_or_b32 v172, s14, 8, v186
	v_add_u32_e32 v176, s15, v184
	v_ashrrev_i32_e32 v173, 31, v172
	v_lshlrev_b64 v[202:203], 1, v[172:173]
	v_ashrrev_i32_e32 v177, 31, v176
	v_lshl_add_u64 v[174:175], s[22:23], 0, v[202:203]
	v_lshlrev_b64 v[204:205], 11, v[176:177]
	v_lshl_add_u64 v[128:129], v[174:175], 0, v[204:205]
	global_load_dwordx4 v[194:197], v[128:129], off
	global_load_dwordx4 v[198:201], v[128:129], off offset:256
	v_or_b32_e32 v128, 16, v176
	v_or_b32_e32 v130, 32, v176
	v_or_b32_e32 v132, 48, v176
	v_ashrrev_i32_e32 v129, 31, v128
	v_ashrrev_i32_e32 v131, 31, v130
	v_ashrrev_i32_e32 v133, 31, v132
	v_lshlrev_b64 v[182:183], 11, v[128:129]
	v_lshlrev_b64 v[180:181], 11, v[130:131]
	v_lshlrev_b64 v[178:179], 11, v[132:133]
	v_lshl_add_u64 v[128:129], v[174:175], 0, v[182:183]
	v_lshl_add_u64 v[130:131], v[174:175], 0, v[180:181]
	v_lshl_add_u64 v[192:193], v[174:175], 0, v[178:179]
	global_load_dwordx4 v[148:151], v[128:129], off
	global_load_dwordx4 v[144:147], v[128:129], off offset:256
	global_load_dwordx4 v[140:143], v[130:131], off
	global_load_dwordx4 v[136:139], v[130:131], off offset:256
	global_load_dwordx4 v[132:135], v[192:193], off
	s_nop 0
	global_load_dwordx4 v[128:131], v[192:193], off offset:256
	v_and_b32_e32 v193, 64, v159
	v_xor_b32_e32 v192, 16, v159
	v_add_u32_e32 v193, 64, v193
	v_xor_b32_e32 v206, 32, v159
	v_cmp_lt_i32_e32 vcc, v192, v193
	v_lshl_add_u64 v[204:205], s[22:23], 0, v[204:205]
	v_lshl_add_u64 v[202:203], v[204:205], 0, v[202:203]
	v_cndmask_b32_e32 v192, v159, v192, vcc
	v_cmp_lt_i32_e32 vcc, v206, v193
	v_lshlrev_b32_e32 v192, 2, v192
	s_waitcnt vmcnt(0)
	v_lshlrev_b32_e32 v204, 16, v194
	v_and_b32_e32 v205, 0xffff0000, v194
	v_lshlrev_b32_e32 v194, 16, v195
	v_and_b32_e32 v195, 0xffff0000, v195
	v_cndmask_b32_e32 v193, v159, v206, vcc
	v_lshlrev_b32_e32 v206, 16, v196
	v_and_b32_e32 v207, 0xffff0000, v196
	v_lshlrev_b32_e32 v196, 16, v197
	v_and_b32_e32 v197, 0xffff0000, v197
	v_lshlrev_b32_e32 v210, 16, v200
	v_and_b32_e32 v211, 0xffff0000, v200
	v_lshlrev_b32_e32 v200, 16, v201
	v_and_b32_e32 v201, 0xffff0000, v201
	v_pk_add_f32 v[126:127], v[126:127], v[194:195]
	v_pk_add_f32 v[124:125], v[124:125], v[204:205]
	v_pk_add_f32 v[122:123], v[122:123], v[196:197]
	v_pk_add_f32 v[196:197], v[114:115], v[200:201]
	v_pk_mul_f32 v[114:115], v[126:127], v[126:127]
	v_pk_add_f32 v[120:121], v[120:121], v[206:207]
	v_pk_fma_f32 v[114:115], v[124:125], v[124:125], v[114:115]
	v_lshlrev_b32_e32 v208, 16, v198
	v_and_b32_e32 v209, 0xffff0000, v198
	v_pk_fma_f32 v[114:115], v[120:121], v[120:121], v[114:115]
	v_lshlrev_b32_e32 v198, 16, v199
	v_and_b32_e32 v199, 0xffff0000, v199
	v_pk_add_f32 v[116:117], v[116:117], v[208:209]
	v_pk_fma_f32 v[114:115], v[122:123], v[122:123], v[114:115]
	v_pk_add_f32 v[118:119], v[118:119], v[198:199]
	v_pk_fma_f32 v[114:115], v[116:117], v[116:117], v[114:115]
	v_pk_add_f32 v[194:195], v[112:113], v[210:211]
	v_pk_fma_f32 v[114:115], v[118:119], v[118:119], v[114:115]
	v_cvt_pk_bf16_f32 v112, v124, v125
	v_cvt_pk_bf16_f32 v113, v126, v127
	s_nop 0
	v_pk_fma_f32 v[114:115], v[194:195], v[194:195], v[114:115]
	s_nop 0
	v_pk_fma_f32 v[114:115], v[196:197], v[196:197], v[114:115]
	s_nop 0
	v_add_f32_e32 v124, v114, v115
	ds_bpermute_b32 v125, v192, v124
	v_cvt_pk_bf16_f32 v114, v120, v121
	v_cvt_pk_bf16_f32 v115, v122, v123
	global_store_dwordx4 v[202:203], v[112:115], off sc1
	v_cvt_pk_bf16_f32 v116, v116, v117
	v_cvt_pk_bf16_f32 v117, v118, v119
	v_cvt_pk_bf16_f32 v118, v194, v195
	v_cvt_pk_bf16_f32 v119, v196, v197
	global_store_dwordx4 v[202:203], v[116:119], off offset:256 sc1
	s_waitcnt lgkmcnt(0)
	v_add_f32_e32 v113, v124, v125
	v_lshlrev_b32_e32 v112, 2, v193
	ds_bpermute_b32 v114, v112, v113
	s_and_saveexec_b64 s[56:57], s[6:7]
	s_cbranch_execz .LBB0_1016
	s_waitcnt lgkmcnt(0)
	v_add_f32_e32 v113, v113, v114
	ds_write_b32 v187, v113
.LBB0_1016:
	s_or_b64 exec, exec, s[56:57]
	v_lshlrev_b32_e32 v116, 16, v149
	v_and_b32_e32 v117, 0xffff0000, v149
	s_waitcnt lgkmcnt(0)
	v_lshlrev_b32_e32 v114, 16, v148
	v_and_b32_e32 v115, 0xffff0000, v148
	v_pk_add_f32 v[110:111], v[110:111], v[116:117]
	v_pk_add_f32 v[114:115], v[108:109], v[114:115]
	v_pk_mul_f32 v[116:117], v[110:111], v[110:111]
	v_cvt_pk_bf16_f32 v108, v114, v115
	v_cvt_pk_bf16_f32 v109, v110, v111
	v_lshlrev_b32_e32 v110, 16, v150
	v_and_b32_e32 v111, 0xffff0000, v150
	v_pk_fma_f32 v[114:115], v[114:115], v[114:115], v[116:117]
	v_pk_add_f32 v[104:105], v[104:105], v[110:111]
	s_nop 0
	v_pk_fma_f32 v[114:115], v[104:105], v[104:105], v[114:115]
	v_cvt_pk_bf16_f32 v110, v104, v105
	v_lshlrev_b32_e32 v104, 16, v151
	v_and_b32_e32 v105, 0xffff0000, v151
	v_pk_add_f32 v[104:105], v[106:107], v[104:105]
	s_nop 0
	v_pk_fma_f32 v[106:107], v[104:105], v[104:105], v[114:115]
	v_cvt_pk_bf16_f32 v111, v104, v105
	v_lshlrev_b32_e32 v104, 16, v144
	v_and_b32_e32 v105, 0xffff0000, v144
	v_pk_add_f32 v[100:101], v[100:101], v[104:105]
	s_nop 0
	v_pk_fma_f32 v[104:105], v[100:101], v[100:101], v[106:107]
	v_lshlrev_b32_e32 v106, 16, v145
	v_and_b32_e32 v107, 0xffff0000, v145
	v_pk_add_f32 v[102:103], v[102:103], v[106:107]
	v_lshlrev_b32_e32 v106, 16, v146
	v_and_b32_e32 v107, 0xffff0000, v146
	v_pk_fma_f32 v[104:105], v[102:103], v[102:103], v[104:105]
	v_pk_add_f32 v[106:107], v[96:97], v[106:107]
	s_nop 0
	v_pk_fma_f32 v[96:97], v[106:107], v[106:107], v[104:105]
	v_lshlrev_b32_e32 v104, 16, v147
	v_and_b32_e32 v105, 0xffff0000, v147
	v_pk_add_f32 v[104:105], v[98:99], v[104:105]
	s_nop 0
	v_pk_fma_f32 v[96:97], v[104:105], v[104:105], v[96:97]
	s_nop 0
	v_add_f32_e32 v99, v96, v97
	ds_bpermute_b32 v113, v192, v99
	v_lshl_add_u64 v[96:97], s[22:23], 0, v[182:183]
	v_lshl_add_u64 v[114:115], v[172:173], 1, v[96:97]
	global_store_dwordx4 v[114:115], v[108:111], off sc1
	v_cvt_pk_bf16_f32 v98, v100, v101
	s_waitcnt lgkmcnt(0)
	v_add_f32_e32 v96, v99, v113
	ds_bpermute_b32 v97, v112, v96
	v_cvt_pk_bf16_f32 v99, v102, v103
	v_cvt_pk_bf16_f32 v100, v106, v107
	v_cvt_pk_bf16_f32 v101, v104, v105
	global_store_dwordx4 v[114:115], v[98:101], off offset:256 sc1
	s_and_saveexec_b64 s[56:57], s[6:7]
	s_cbranch_execz .LBB0_1018
	s_waitcnt lgkmcnt(0)
	v_add_f32_e32 v96, v96, v97
	ds_write_b32 v187, v96 offset:256
.LBB0_1018:
	s_or_b64 exec, exec, s[56:57]
	v_lshlrev_b32_e32 v98, 16, v141
	v_and_b32_e32 v99, 0xffff0000, v141
	v_lshlrev_b32_e32 v96, 16, v140
	s_waitcnt lgkmcnt(0)
	v_and_b32_e32 v97, 0xffff0000, v140
	v_pk_add_f32 v[94:95], v[94:95], v[98:99]
	v_pk_add_f32 v[96:97], v[92:93], v[96:97]
	v_pk_mul_f32 v[98:99], v[94:95], v[94:95]
	v_cvt_pk_bf16_f32 v92, v96, v97
	v_cvt_pk_bf16_f32 v93, v94, v95
	v_lshlrev_b32_e32 v94, 16, v142
	v_and_b32_e32 v95, 0xffff0000, v142
	v_pk_fma_f32 v[96:97], v[96:97], v[96:97], v[98:99]
	v_pk_add_f32 v[88:89], v[88:89], v[94:95]
	s_nop 0
	v_pk_fma_f32 v[96:97], v[88:89], v[88:89], v[96:97]
	v_cvt_pk_bf16_f32 v94, v88, v89
	v_lshlrev_b32_e32 v88, 16, v143
	v_and_b32_e32 v89, 0xffff0000, v143
	v_pk_add_f32 v[88:89], v[90:91], v[88:89]
	s_nop 0
	v_pk_fma_f32 v[90:91], v[88:89], v[88:89], v[96:97]
	v_cvt_pk_bf16_f32 v95, v88, v89
	v_lshlrev_b32_e32 v88, 16, v136
	v_and_b32_e32 v89, 0xffff0000, v136
	v_pk_add_f32 v[84:85], v[84:85], v[88:89]
	s_nop 0
	v_pk_fma_f32 v[88:89], v[84:85], v[84:85], v[90:91]
	v_lshlrev_b32_e32 v90, 16, v137
	v_and_b32_e32 v91, 0xffff0000, v137
	v_pk_add_f32 v[86:87], v[86:87], v[90:91]
	v_lshlrev_b32_e32 v90, 16, v138
	v_and_b32_e32 v91, 0xffff0000, v138
	v_pk_fma_f32 v[88:89], v[86:87], v[86:87], v[88:89]
	v_pk_add_f32 v[90:91], v[80:81], v[90:91]
	s_nop 0
	v_pk_fma_f32 v[80:81], v[90:91], v[90:91], v[88:89]
	v_lshlrev_b32_e32 v88, 16, v139
	v_and_b32_e32 v89, 0xffff0000, v139
	v_pk_add_f32 v[88:89], v[82:83], v[88:89]
	s_nop 0
	v_pk_fma_f32 v[80:81], v[88:89], v[88:89], v[80:81]
	s_nop 0
	v_add_f32_e32 v83, v80, v81
	ds_bpermute_b32 v98, v192, v83
	v_lshl_add_u64 v[80:81], s[22:23], 0, v[180:181]
	v_lshl_add_u64 v[96:97], v[172:173], 1, v[80:81]
	global_store_dwordx4 v[96:97], v[92:95], off sc1
	v_cvt_pk_bf16_f32 v82, v84, v85
	s_waitcnt lgkmcnt(0)
	v_add_f32_e32 v80, v83, v98
	ds_bpermute_b32 v81, v112, v80
	v_cvt_pk_bf16_f32 v83, v86, v87
	v_cvt_pk_bf16_f32 v84, v90, v91
	v_cvt_pk_bf16_f32 v85, v88, v89
	global_store_dwordx4 v[96:97], v[82:85], off offset:256 sc1
	s_and_saveexec_b64 s[56:57], s[6:7]
	s_cbranch_execz .LBB0_1020
	s_waitcnt lgkmcnt(0)
	v_add_f32_e32 v80, v80, v81
	ds_write_b32 v187, v80 offset:512
.LBB0_1020:
	s_or_b64 exec, exec, s[56:57]
	v_lshlrev_b32_e32 v82, 16, v133
	v_and_b32_e32 v83, 0xffff0000, v133
	v_lshlrev_b32_e32 v80, 16, v132
	s_waitcnt lgkmcnt(0)
	v_and_b32_e32 v81, 0xffff0000, v132
	v_pk_add_f32 v[78:79], v[78:79], v[82:83]
	v_pk_add_f32 v[80:81], v[76:77], v[80:81]
	v_pk_mul_f32 v[82:83], v[78:79], v[78:79]
	v_cvt_pk_bf16_f32 v76, v80, v81
	v_cvt_pk_bf16_f32 v77, v78, v79
	v_lshlrev_b32_e32 v78, 16, v134
	v_and_b32_e32 v79, 0xffff0000, v134
	v_pk_fma_f32 v[80:81], v[80:81], v[80:81], v[82:83]
	v_pk_add_f32 v[72:73], v[72:73], v[78:79]
	s_nop 0
	v_pk_fma_f32 v[80:81], v[72:73], v[72:73], v[80:81]
	v_cvt_pk_bf16_f32 v78, v72, v73
	v_lshlrev_b32_e32 v72, 16, v135
	v_and_b32_e32 v73, 0xffff0000, v135
	v_pk_add_f32 v[72:73], v[74:75], v[72:73]
	s_nop 0
	v_pk_fma_f32 v[74:75], v[72:73], v[72:73], v[80:81]
	v_cvt_pk_bf16_f32 v79, v72, v73
	v_lshlrev_b32_e32 v72, 16, v128
	v_and_b32_e32 v73, 0xffff0000, v128
	v_pk_add_f32 v[68:69], v[68:69], v[72:73]
	s_nop 0
	v_pk_fma_f32 v[72:73], v[68:69], v[68:69], v[74:75]
	v_lshlrev_b32_e32 v74, 16, v129
	v_and_b32_e32 v75, 0xffff0000, v129
	v_pk_add_f32 v[70:71], v[70:71], v[74:75]
	v_lshlrev_b32_e32 v74, 16, v130
	v_and_b32_e32 v75, 0xffff0000, v130
	v_pk_fma_f32 v[72:73], v[70:71], v[70:71], v[72:73]
	v_pk_add_f32 v[74:75], v[64:65], v[74:75]
	s_nop 0
	v_pk_fma_f32 v[64:65], v[74:75], v[74:75], v[72:73]
	v_lshlrev_b32_e32 v72, 16, v131
	v_and_b32_e32 v73, 0xffff0000, v131
	v_pk_add_f32 v[72:73], v[66:67], v[72:73]
	s_nop 0
	v_pk_fma_f32 v[64:65], v[72:73], v[72:73], v[64:65]
	s_nop 0
	v_add_f32_e32 v67, v64, v65
	ds_bpermute_b32 v82, v192, v67
	v_lshl_add_u64 v[64:65], s[22:23], 0, v[178:179]
	v_lshl_add_u64 v[80:81], v[172:173], 1, v[64:65]
	global_store_dwordx4 v[80:81], v[76:79], off sc1
	v_cvt_pk_bf16_f32 v66, v68, v69
	s_waitcnt lgkmcnt(0)
	v_add_f32_e32 v64, v67, v82
	ds_bpermute_b32 v65, v112, v64
	v_cvt_pk_bf16_f32 v67, v70, v71
	v_cvt_pk_bf16_f32 v68, v74, v75
	v_cvt_pk_bf16_f32 v69, v72, v73
	global_store_dwordx4 v[80:81], v[66:69], off offset:256 sc1
	s_and_saveexec_b64 s[56:57], s[6:7]
	s_cbranch_execz .LBB0_1022
	s_waitcnt lgkmcnt(0)
	v_add_f32_e32 v64, v64, v65
	ds_write_b32 v187, v64 offset:768
.LBB0_1022:
	s_or_b64 exec, exec, s[56:57]
	s_waitcnt lgkmcnt(0)
	v_lshlrev_b64 v[64:65], 11, v[176:177]
	v_lshl_add_u64 v[102:103], v[64:65], 0, s[16:17]
	v_lshl_add_u64 v[66:67], v[174:175], 0, v[102:103]
	global_load_dwordx4 v[94:97], v[66:67], off
	global_load_dwordx4 v[98:101], v[66:67], off offset:256
	v_lshl_add_u64 v[92:93], v[64:65], 0, s[30:31]
	v_lshl_add_u64 v[90:91], v[64:65], 0, s[44:45]
	v_lshl_add_u64 v[88:89], v[64:65], 0, s[46:47]
	v_lshl_add_u64 v[64:65], v[174:175], 0, v[92:93]
	v_lshl_add_u64 v[66:67], v[174:175], 0, v[90:91]
	v_lshl_add_u64 v[104:105], v[174:175], 0, v[88:89]
	global_load_dwordx4 v[84:87], v[64:65], off
	global_load_dwordx4 v[80:83], v[64:65], off offset:256
	global_load_dwordx4 v[76:79], v[66:67], off
	global_load_dwordx4 v[72:75], v[66:67], off offset:256
	global_load_dwordx4 v[68:71], v[104:105], off
	s_nop 0
	global_load_dwordx4 v[64:67], v[104:105], off offset:256
	s_waitcnt vmcnt(7)
	v_lshlrev_b32_e32 v104, 16, v94
	v_and_b32_e32 v105, 0xffff0000, v94
	v_lshlrev_b32_e32 v94, 16, v95
	v_and_b32_e32 v95, 0xffff0000, v95
	v_lshlrev_b32_e32 v106, 16, v96
	v_and_b32_e32 v107, 0xffff0000, v96
	v_lshlrev_b32_e32 v96, 16, v97
	v_and_b32_e32 v97, 0xffff0000, v97
	s_waitcnt vmcnt(6)
	v_lshlrev_b32_e32 v108, 16, v98
	v_and_b32_e32 v109, 0xffff0000, v98
	v_lshlrev_b32_e32 v98, 16, v99
	v_and_b32_e32 v99, 0xffff0000, v99
	v_lshlrev_b32_e32 v110, 16, v100
	v_and_b32_e32 v111, 0xffff0000, v100
	v_pk_add_f32 v[62:63], v[62:63], v[94:95]
	v_pk_add_f32 v[60:61], v[60:61], v[104:105]
	v_pk_add_f32 v[58:59], v[58:59], v[96:97]
	v_pk_add_f32 v[96:97], v[54:55], v[98:99]
	v_pk_add_f32 v[98:99], v[48:49], v[110:111]
	v_pk_mul_f32 v[48:49], v[62:63], v[62:63]
	v_pk_add_f32 v[56:57], v[56:57], v[106:107]
	v_pk_fma_f32 v[48:49], v[60:61], v[60:61], v[48:49]
	v_pk_add_f32 v[94:95], v[52:53], v[108:109]
	v_pk_fma_f32 v[48:49], v[56:57], v[56:57], v[48:49]
	v_lshlrev_b32_e32 v100, 16, v101
	v_pk_fma_f32 v[48:49], v[58:59], v[58:59], v[48:49]
	v_and_b32_e32 v101, 0xffff0000, v101
	v_pk_fma_f32 v[48:49], v[94:95], v[94:95], v[48:49]
	v_cvt_pk_bf16_f32 v52, v60, v61
	v_cvt_pk_bf16_f32 v53, v62, v63
	v_cvt_pk_bf16_f32 v54, v56, v57
	v_pk_add_f32 v[56:57], v[50:51], v[100:101]
	v_pk_fma_f32 v[48:49], v[96:97], v[96:97], v[48:49]
	v_cvt_pk_bf16_f32 v55, v58, v59
	s_nop 0
	v_pk_fma_f32 v[48:49], v[98:99], v[98:99], v[48:49]
	s_nop 0
	v_pk_fma_f32 v[48:49], v[56:57], v[56:57], v[48:49]
	s_nop 0
	v_add_f32_e32 v51, v48, v49
	ds_bpermute_b32 v60, v192, v51
	v_lshl_add_u64 v[48:49], s[22:23], 0, v[102:103]
	v_lshl_add_u64 v[58:59], v[172:173], 1, v[48:49]
	global_store_dwordx4 v[58:59], v[52:55], off sc1
	v_cvt_pk_bf16_f32 v50, v94, v95
	s_waitcnt lgkmcnt(0)
	v_add_f32_e32 v48, v51, v60
	ds_bpermute_b32 v49, v112, v48
	v_cvt_pk_bf16_f32 v51, v96, v97
	v_cvt_pk_bf16_f32 v52, v98, v99
	v_cvt_pk_bf16_f32 v53, v56, v57
	global_store_dwordx4 v[58:59], v[50:53], off offset:256 sc1
	s_and_saveexec_b64 s[56:57], s[6:7]
	s_cbranch_execz .LBB0_1024
	s_waitcnt lgkmcnt(0)
	v_add_f32_e32 v48, v48, v49
	ds_write_b32 v187, v48 offset:2048
.LBB0_1024:
	s_or_b64 exec, exec, s[56:57]
	s_waitcnt vmcnt(7)
	v_lshlrev_b32_e32 v50, 16, v85
	v_and_b32_e32 v51, 0xffff0000, v85
	v_lshlrev_b32_e32 v48, 16, v84
	s_waitcnt lgkmcnt(0)
	v_and_b32_e32 v49, 0xffff0000, v84
	v_pk_add_f32 v[46:47], v[46:47], v[50:51]
	v_pk_add_f32 v[48:49], v[44:45], v[48:49]
	v_pk_mul_f32 v[50:51], v[46:47], v[46:47]
	v_cvt_pk_bf16_f32 v44, v48, v49
	v_cvt_pk_bf16_f32 v45, v46, v47
	v_lshlrev_b32_e32 v46, 16, v86
	v_and_b32_e32 v47, 0xffff0000, v86
	v_pk_fma_f32 v[48:49], v[48:49], v[48:49], v[50:51]
	v_pk_add_f32 v[40:41], v[40:41], v[46:47]
	s_nop 0
	v_pk_fma_f32 v[48:49], v[40:41], v[40:41], v[48:49]
	v_cvt_pk_bf16_f32 v46, v40, v41
	v_lshlrev_b32_e32 v40, 16, v87
	v_and_b32_e32 v41, 0xffff0000, v87
	v_pk_add_f32 v[40:41], v[42:43], v[40:41]
	s_nop 0
	v_pk_fma_f32 v[42:43], v[40:41], v[40:41], v[48:49]
	v_cvt_pk_bf16_f32 v47, v40, v41
	s_waitcnt vmcnt(6)
	v_lshlrev_b32_e32 v40, 16, v80
	v_and_b32_e32 v41, 0xffff0000, v80
	v_pk_add_f32 v[36:37], v[36:37], v[40:41]
	s_nop 0
	v_pk_fma_f32 v[40:41], v[36:37], v[36:37], v[42:43]
	v_lshlrev_b32_e32 v42, 16, v81
	v_and_b32_e32 v43, 0xffff0000, v81
	v_pk_add_f32 v[38:39], v[38:39], v[42:43]
	v_lshlrev_b32_e32 v42, 16, v82
	v_and_b32_e32 v43, 0xffff0000, v82
	v_pk_fma_f32 v[40:41], v[38:39], v[38:39], v[40:41]
	v_pk_add_f32 v[42:43], v[32:33], v[42:43]
	s_nop 0
	v_pk_fma_f32 v[32:33], v[42:43], v[42:43], v[40:41]
	v_lshlrev_b32_e32 v40, 16, v83
	v_and_b32_e32 v41, 0xffff0000, v83
	v_pk_add_f32 v[40:41], v[34:35], v[40:41]
	s_nop 0
	v_pk_fma_f32 v[32:33], v[40:41], v[40:41], v[32:33]
	s_nop 0
	v_add_f32_e32 v35, v32, v33
	ds_bpermute_b32 v50, v192, v35
	v_lshl_add_u64 v[32:33], s[22:23], 0, v[92:93]
	v_lshl_add_u64 v[48:49], v[172:173], 1, v[32:33]
	global_store_dwordx4 v[48:49], v[44:47], off sc1
	v_cvt_pk_bf16_f32 v34, v36, v37
	s_waitcnt lgkmcnt(0)
	v_add_f32_e32 v32, v35, v50
	ds_bpermute_b32 v33, v112, v32
	v_cvt_pk_bf16_f32 v35, v38, v39
	v_cvt_pk_bf16_f32 v36, v42, v43
	v_cvt_pk_bf16_f32 v37, v40, v41
	global_store_dwordx4 v[48:49], v[34:37], off offset:256 sc1
	s_and_saveexec_b64 s[56:57], s[6:7]
	s_cbranch_execz .LBB0_1026
	s_waitcnt lgkmcnt(0)
	v_add_f32_e32 v32, v32, v33
	ds_write_b32 v187, v32 offset:2304
.LBB0_1026:
	s_or_b64 exec, exec, s[56:57]
	s_waitcnt vmcnt(7)
	v_lshlrev_b32_e32 v34, 16, v77
	v_and_b32_e32 v35, 0xffff0000, v77
	v_lshlrev_b32_e32 v32, 16, v76
	s_waitcnt lgkmcnt(0)
	v_and_b32_e32 v33, 0xffff0000, v76
	v_pk_add_f32 v[30:31], v[30:31], v[34:35]
	v_pk_add_f32 v[32:33], v[28:29], v[32:33]
	v_pk_mul_f32 v[34:35], v[30:31], v[30:31]
	v_cvt_pk_bf16_f32 v28, v32, v33
	v_cvt_pk_bf16_f32 v29, v30, v31
	v_lshlrev_b32_e32 v30, 16, v78
	v_and_b32_e32 v31, 0xffff0000, v78
	v_pk_fma_f32 v[32:33], v[32:33], v[32:33], v[34:35]
	v_pk_add_f32 v[24:25], v[24:25], v[30:31]
	s_nop 0
	v_pk_fma_f32 v[32:33], v[24:25], v[24:25], v[32:33]
	v_cvt_pk_bf16_f32 v30, v24, v25
	v_lshlrev_b32_e32 v24, 16, v79
	v_and_b32_e32 v25, 0xffff0000, v79
	v_pk_add_f32 v[24:25], v[26:27], v[24:25]
	s_nop 0
	v_pk_fma_f32 v[26:27], v[24:25], v[24:25], v[32:33]
	v_cvt_pk_bf16_f32 v31, v24, v25
	s_waitcnt vmcnt(6)
	v_lshlrev_b32_e32 v24, 16, v72
	v_and_b32_e32 v25, 0xffff0000, v72
	v_pk_add_f32 v[20:21], v[20:21], v[24:25]
	s_nop 0
	v_pk_fma_f32 v[24:25], v[20:21], v[20:21], v[26:27]
	v_lshlrev_b32_e32 v26, 16, v73
	v_and_b32_e32 v27, 0xffff0000, v73
	v_pk_add_f32 v[22:23], v[22:23], v[26:27]
	v_lshlrev_b32_e32 v26, 16, v74
	v_and_b32_e32 v27, 0xffff0000, v74
	v_pk_fma_f32 v[24:25], v[22:23], v[22:23], v[24:25]
	v_pk_add_f32 v[26:27], v[16:17], v[26:27]
	s_nop 0
	v_pk_fma_f32 v[16:17], v[26:27], v[26:27], v[24:25]
	v_lshlrev_b32_e32 v24, 16, v75
	v_and_b32_e32 v25, 0xffff0000, v75
	v_pk_add_f32 v[24:25], v[18:19], v[24:25]
	s_nop 0
	v_pk_fma_f32 v[16:17], v[24:25], v[24:25], v[16:17]
	s_nop 0
	v_add_f32_e32 v19, v16, v17
	ds_bpermute_b32 v34, v192, v19
	v_lshl_add_u64 v[16:17], s[22:23], 0, v[90:91]
	v_lshl_add_u64 v[32:33], v[172:173], 1, v[16:17]
	global_store_dwordx4 v[32:33], v[28:31], off sc1
	v_cvt_pk_bf16_f32 v18, v20, v21
	s_waitcnt lgkmcnt(0)
	v_add_f32_e32 v16, v19, v34
	ds_bpermute_b32 v17, v112, v16
	v_cvt_pk_bf16_f32 v19, v22, v23
	v_cvt_pk_bf16_f32 v20, v26, v27
	v_cvt_pk_bf16_f32 v21, v24, v25
	global_store_dwordx4 v[32:33], v[18:21], off offset:256 sc1
	s_and_saveexec_b64 s[56:57], s[6:7]
	s_cbranch_execz .LBB0_1028
	s_waitcnt lgkmcnt(0)
	v_add_f32_e32 v16, v16, v17
	ds_write_b32 v187, v16 offset:2560
.LBB0_1028:
	s_or_b64 exec, exec, s[56:57]
	s_waitcnt vmcnt(7)
	v_lshlrev_b32_e32 v18, 16, v69
	v_and_b32_e32 v19, 0xffff0000, v69
	v_lshlrev_b32_e32 v16, 16, v68
	s_waitcnt lgkmcnt(0)
	v_and_b32_e32 v17, 0xffff0000, v68
	v_pk_add_f32 v[14:15], v[14:15], v[18:19]
	v_pk_add_f32 v[16:17], v[12:13], v[16:17]
	v_pk_mul_f32 v[18:19], v[14:15], v[14:15]
	v_cvt_pk_bf16_f32 v12, v16, v17
	v_cvt_pk_bf16_f32 v13, v14, v15
	v_lshlrev_b32_e32 v14, 16, v70
	v_and_b32_e32 v15, 0xffff0000, v70
	v_pk_fma_f32 v[16:17], v[16:17], v[16:17], v[18:19]
	v_pk_add_f32 v[8:9], v[8:9], v[14:15]
	s_nop 0
	v_pk_fma_f32 v[16:17], v[8:9], v[8:9], v[16:17]
	v_cvt_pk_bf16_f32 v14, v8, v9
	v_lshlrev_b32_e32 v8, 16, v71
	v_and_b32_e32 v9, 0xffff0000, v71
	v_pk_add_f32 v[8:9], v[10:11], v[8:9]
	s_nop 0
	v_pk_fma_f32 v[10:11], v[8:9], v[8:9], v[16:17]
	v_cvt_pk_bf16_f32 v15, v8, v9
	s_waitcnt vmcnt(6)
	v_lshlrev_b32_e32 v8, 16, v64
	v_and_b32_e32 v9, 0xffff0000, v64
	v_pk_add_f32 v[4:5], v[4:5], v[8:9]
	s_nop 0
	v_pk_fma_f32 v[8:9], v[4:5], v[4:5], v[10:11]
	v_lshlrev_b32_e32 v10, 16, v65
	v_and_b32_e32 v11, 0xffff0000, v65
	v_pk_add_f32 v[6:7], v[6:7], v[10:11]
	v_lshlrev_b32_e32 v10, 16, v66
	v_and_b32_e32 v11, 0xffff0000, v66
	v_pk_fma_f32 v[8:9], v[6:7], v[6:7], v[8:9]
	v_pk_add_f32 v[10:11], v[0:1], v[10:11]
	s_nop 0
	v_pk_fma_f32 v[0:1], v[10:11], v[10:11], v[8:9]
	v_lshlrev_b32_e32 v8, 16, v67
	v_and_b32_e32 v9, 0xffff0000, v67
	v_pk_add_f32 v[8:9], v[2:3], v[8:9]
	s_nop 0
	v_pk_fma_f32 v[0:1], v[8:9], v[8:9], v[0:1]
	s_nop 0
	v_add_f32_e32 v3, v0, v1
	ds_bpermute_b32 v18, v192, v3
	v_lshl_add_u64 v[0:1], s[22:23], 0, v[88:89]
	v_lshl_add_u64 v[16:17], v[172:173], 1, v[0:1]
	global_store_dwordx4 v[16:17], v[12:15], off sc1
	v_cvt_pk_bf16_f32 v2, v4, v5
	s_waitcnt lgkmcnt(0)
	v_add_f32_e32 v0, v3, v18
	ds_bpermute_b32 v1, v112, v0
	v_cvt_pk_bf16_f32 v3, v6, v7
	v_cvt_pk_bf16_f32 v4, v10, v11
	v_cvt_pk_bf16_f32 v5, v8, v9
	global_store_dwordx4 v[16:17], v[2:5], off offset:256 sc1
	s_and_saveexec_b64 s[56:57], s[6:7]
	s_cbranch_execz .LBB0_1030
	s_waitcnt lgkmcnt(0)
	v_add_f32_e32 v0, v0, v1
	ds_write_b32 v187, v0 offset:2816
.LBB0_1030:
	s_or_b64 exec, exec, s[56:57]
	s_waitcnt lgkmcnt(0)
	s_barrier
	s_and_saveexec_b64 s[56:57], s[10:11]
	s_cbranch_execz .LBB0_1032
	s_waitcnt lgkmcnt(0)
	ds_read_b128 v[0:3], v191
	v_or_b32_e32 v4, s15, v157
	v_ashrrev_i32_e32 v5, 31, v4
	s_ashr_i32 s15, s14, 31
	s_waitcnt lgkmcnt(0)
	v_mov_b32_e32 v6, v1
	v_mov_b32_e32 v7, v2
	v_mov_b32_e32 v1, v3
	v_pk_add_f32 v[0:1], v[6:7], v[0:1]
	s_nop 0
	v_add_f32_e32 v2, v0, v1
	v_lshl_add_u64 v[0:1], v[4:5], 4, s[24:25]
	v_lshl_add_u64 v[0:1], s[14:15], 2, v[0:1]
	global_store_dword v[0:1], v2, off sc1

.LBB0_1184:
	s_lshl_b32 s13, s13, 8
	v_lshl_or_b32 v172, s12, 8, v186
	v_add_u32_e32 v176, s13, v184
	v_ashrrev_i32_e32 v173, 31, v172
	v_lshlrev_b64 v[202:203], 1, v[172:173]
	v_ashrrev_i32_e32 v177, 31, v176
	v_lshl_add_u64 v[174:175], s[16:17], 0, v[202:203]
	v_lshlrev_b64 v[204:205], 11, v[176:177]
	v_lshl_add_u64 v[128:129], v[174:175], 0, v[204:205]
	global_load_dwordx4 v[194:197], v[128:129], off
	global_load_dwordx4 v[198:201], v[128:129], off offset:256
	v_or_b32_e32 v128, 16, v176
	v_or_b32_e32 v130, 32, v176
	v_or_b32_e32 v132, 48, v176
	v_ashrrev_i32_e32 v129, 31, v128
	v_ashrrev_i32_e32 v131, 31, v130
	v_ashrrev_i32_e32 v133, 31, v132
	v_lshlrev_b64 v[182:183], 11, v[128:129]
	v_lshlrev_b64 v[180:181], 11, v[130:131]
	v_lshlrev_b64 v[178:179], 11, v[132:133]
	v_lshl_add_u64 v[128:129], v[174:175], 0, v[182:183]
	v_lshl_add_u64 v[130:131], v[174:175], 0, v[180:181]
	v_lshl_add_u64 v[192:193], v[174:175], 0, v[178:179]
	global_load_dwordx4 v[148:151], v[128:129], off
	global_load_dwordx4 v[144:147], v[128:129], off offset:256
	global_load_dwordx4 v[140:143], v[130:131], off
	global_load_dwordx4 v[136:139], v[130:131], off offset:256
	global_load_dwordx4 v[132:135], v[192:193], off
	s_nop 0
	global_load_dwordx4 v[128:131], v[192:193], off offset:256
	v_and_b32_e32 v193, 64, v159
	v_xor_b32_e32 v192, 16, v159
	v_add_u32_e32 v193, 64, v193
	v_xor_b32_e32 v206, 32, v159
	v_cmp_lt_i32_e32 vcc, v192, v193
	v_lshl_add_u64 v[204:205], s[16:17], 0, v[204:205]
	v_lshl_add_u64 v[202:203], v[204:205], 0, v[202:203]
	v_cndmask_b32_e32 v192, v159, v192, vcc
	v_cmp_lt_i32_e32 vcc, v206, v193
	v_lshlrev_b32_e32 v192, 2, v192
	s_waitcnt vmcnt(0)
	v_lshlrev_b32_e32 v204, 16, v194
	v_and_b32_e32 v205, 0xffff0000, v194
	v_lshlrev_b32_e32 v194, 16, v195
	v_and_b32_e32 v195, 0xffff0000, v195
	v_cndmask_b32_e32 v193, v159, v206, vcc
	v_lshlrev_b32_e32 v206, 16, v196
	v_and_b32_e32 v207, 0xffff0000, v196
	v_lshlrev_b32_e32 v196, 16, v197
	v_and_b32_e32 v197, 0xffff0000, v197
	v_lshlrev_b32_e32 v210, 16, v200
	v_and_b32_e32 v211, 0xffff0000, v200
	v_lshlrev_b32_e32 v200, 16, v201
	v_and_b32_e32 v201, 0xffff0000, v201
	v_pk_fma_f32 v[126:127], v[126:127], 0.5, v[194:195] op_sel_hi:[1,0,1]
	v_pk_fma_f32 v[124:125], v[124:125], 0.5, v[204:205] op_sel_hi:[1,0,1]
	v_pk_fma_f32 v[122:123], v[122:123], 0.5, v[196:197] op_sel_hi:[1,0,1]
	v_pk_fma_f32 v[196:197], v[114:115], 0.5, v[200:201] op_sel_hi:[1,0,1]
	v_pk_mul_f32 v[114:115], v[126:127], v[126:127]
	v_pk_fma_f32 v[120:121], v[120:121], 0.5, v[206:207] op_sel_hi:[1,0,1]
	v_pk_fma_f32 v[114:115], v[124:125], v[124:125], v[114:115]
	v_lshlrev_b32_e32 v208, 16, v198
	v_and_b32_e32 v209, 0xffff0000, v198
	v_pk_fma_f32 v[114:115], v[120:121], v[120:121], v[114:115]
	v_lshlrev_b32_e32 v198, 16, v199
	v_and_b32_e32 v199, 0xffff0000, v199
	v_pk_fma_f32 v[116:117], v[116:117], 0.5, v[208:209] op_sel_hi:[1,0,1]
	v_pk_fma_f32 v[114:115], v[122:123], v[122:123], v[114:115]
	v_pk_fma_f32 v[118:119], v[118:119], 0.5, v[198:199] op_sel_hi:[1,0,1]
	v_pk_fma_f32 v[114:115], v[116:117], v[116:117], v[114:115]
	v_pk_fma_f32 v[194:195], v[112:113], 0.5, v[210:211] op_sel_hi:[1,0,1]
	v_pk_fma_f32 v[114:115], v[118:119], v[118:119], v[114:115]
	v_cvt_pk_bf16_f32 v112, v124, v125
	v_cvt_pk_bf16_f32 v113, v126, v127
	s_nop 0
	v_pk_fma_f32 v[114:115], v[194:195], v[194:195], v[114:115]
	s_nop 0
	v_pk_fma_f32 v[114:115], v[196:197], v[196:197], v[114:115]
	s_nop 0
	v_add_f32_e32 v124, v114, v115
	ds_bpermute_b32 v125, v192, v124
	v_cvt_pk_bf16_f32 v114, v120, v121
	v_cvt_pk_bf16_f32 v115, v122, v123
	global_store_dwordx4 v[202:203], v[112:115], off sc1
	v_cvt_pk_bf16_f32 v116, v116, v117
	v_cvt_pk_bf16_f32 v117, v118, v119
	v_cvt_pk_bf16_f32 v118, v194, v195
	v_cvt_pk_bf16_f32 v119, v196, v197
	global_store_dwordx4 v[202:203], v[116:119], off offset:256 sc1
	s_waitcnt lgkmcnt(0)
	v_add_f32_e32 v113, v124, v125
	v_lshlrev_b32_e32 v112, 2, v193
	ds_bpermute_b32 v114, v112, v113
	s_and_saveexec_b64 s[48:49], s[4:5]
	s_cbranch_execz .LBB0_1186
	s_waitcnt lgkmcnt(0)
	v_add_f32_e32 v113, v113, v114
	ds_write_b32 v187, v113
.LBB0_1186:
	s_or_b64 exec, exec, s[48:49]
	v_lshlrev_b32_e32 v116, 16, v149
	v_and_b32_e32 v117, 0xffff0000, v149
	s_waitcnt lgkmcnt(0)
	v_lshlrev_b32_e32 v114, 16, v148
	v_and_b32_e32 v115, 0xffff0000, v148
	v_pk_fma_f32 v[110:111], v[110:111], 0.5, v[116:117] op_sel_hi:[1,0,1]
	v_pk_fma_f32 v[114:115], v[108:109], 0.5, v[114:115] op_sel_hi:[1,0,1]
	v_pk_mul_f32 v[116:117], v[110:111], v[110:111]
	v_cvt_pk_bf16_f32 v108, v114, v115
	v_cvt_pk_bf16_f32 v109, v110, v111
	v_lshlrev_b32_e32 v110, 16, v150
	v_and_b32_e32 v111, 0xffff0000, v150
	v_pk_fma_f32 v[114:115], v[114:115], v[114:115], v[116:117]
	v_pk_fma_f32 v[104:105], v[104:105], 0.5, v[110:111] op_sel_hi:[1,0,1]
	s_nop 0
	v_pk_fma_f32 v[114:115], v[104:105], v[104:105], v[114:115]
	v_cvt_pk_bf16_f32 v110, v104, v105
	v_lshlrev_b32_e32 v104, 16, v151
	v_and_b32_e32 v105, 0xffff0000, v151
	v_pk_fma_f32 v[104:105], v[106:107], 0.5, v[104:105] op_sel_hi:[1,0,1]
	s_nop 0
	v_pk_fma_f32 v[106:107], v[104:105], v[104:105], v[114:115]
	v_cvt_pk_bf16_f32 v111, v104, v105
	v_lshlrev_b32_e32 v104, 16, v144
	v_and_b32_e32 v105, 0xffff0000, v144
	v_pk_fma_f32 v[100:101], v[100:101], 0.5, v[104:105] op_sel_hi:[1,0,1]
	s_nop 0
	v_pk_fma_f32 v[104:105], v[100:101], v[100:101], v[106:107]
	v_lshlrev_b32_e32 v106, 16, v145
	v_and_b32_e32 v107, 0xffff0000, v145
	v_pk_fma_f32 v[102:103], v[102:103], 0.5, v[106:107] op_sel_hi:[1,0,1]
	v_lshlrev_b32_e32 v106, 16, v146
	v_and_b32_e32 v107, 0xffff0000, v146
	v_pk_fma_f32 v[104:105], v[102:103], v[102:103], v[104:105]
	v_pk_fma_f32 v[106:107], v[96:97], 0.5, v[106:107] op_sel_hi:[1,0,1]
	s_nop 0
	v_pk_fma_f32 v[96:97], v[106:107], v[106:107], v[104:105]
	v_lshlrev_b32_e32 v104, 16, v147
	v_and_b32_e32 v105, 0xffff0000, v147
	v_pk_fma_f32 v[104:105], v[98:99], 0.5, v[104:105] op_sel_hi:[1,0,1]
	s_nop 0
	v_pk_fma_f32 v[96:97], v[104:105], v[104:105], v[96:97]
	s_nop 0
	v_add_f32_e32 v99, v96, v97
	ds_bpermute_b32 v113, v192, v99
	v_lshl_add_u64 v[96:97], s[16:17], 0, v[182:183]
	v_lshl_add_u64 v[114:115], v[172:173], 1, v[96:97]
	global_store_dwordx4 v[114:115], v[108:111], off sc1
	v_cvt_pk_bf16_f32 v98, v100, v101
	s_waitcnt lgkmcnt(0)
	v_add_f32_e32 v96, v99, v113
	ds_bpermute_b32 v97, v112, v96
	v_cvt_pk_bf16_f32 v99, v102, v103
	v_cvt_pk_bf16_f32 v100, v106, v107
	v_cvt_pk_bf16_f32 v101, v104, v105
	global_store_dwordx4 v[114:115], v[98:101], off offset:256 sc1
	s_and_saveexec_b64 s[48:49], s[4:5]
	s_cbranch_execz .LBB0_1188
	s_waitcnt lgkmcnt(0)
	v_add_f32_e32 v96, v96, v97
	ds_write_b32 v187, v96 offset:256
.LBB0_1188:
	s_or_b64 exec, exec, s[48:49]
	v_lshlrev_b32_e32 v98, 16, v141
	v_and_b32_e32 v99, 0xffff0000, v141
	v_lshlrev_b32_e32 v96, 16, v140
	s_waitcnt lgkmcnt(0)
	v_and_b32_e32 v97, 0xffff0000, v140
	v_pk_fma_f32 v[94:95], v[94:95], 0.5, v[98:99] op_sel_hi:[1,0,1]
	v_pk_fma_f32 v[96:97], v[92:93], 0.5, v[96:97] op_sel_hi:[1,0,1]
	v_pk_mul_f32 v[98:99], v[94:95], v[94:95]
	v_cvt_pk_bf16_f32 v92, v96, v97
	v_cvt_pk_bf16_f32 v93, v94, v95
	v_lshlrev_b32_e32 v94, 16, v142
	v_and_b32_e32 v95, 0xffff0000, v142
	v_pk_fma_f32 v[96:97], v[96:97], v[96:97], v[98:99]
	v_pk_fma_f32 v[88:89], v[88:89], 0.5, v[94:95] op_sel_hi:[1,0,1]
	s_nop 0
	v_pk_fma_f32 v[96:97], v[88:89], v[88:89], v[96:97]
	v_cvt_pk_bf16_f32 v94, v88, v89
	v_lshlrev_b32_e32 v88, 16, v143
	v_and_b32_e32 v89, 0xffff0000, v143
	v_pk_fma_f32 v[88:89], v[90:91], 0.5, v[88:89] op_sel_hi:[1,0,1]
	s_nop 0
	v_pk_fma_f32 v[90:91], v[88:89], v[88:89], v[96:97]
	v_cvt_pk_bf16_f32 v95, v88, v89
	v_lshlrev_b32_e32 v88, 16, v136
	v_and_b32_e32 v89, 0xffff0000, v136
	v_pk_fma_f32 v[84:85], v[84:85], 0.5, v[88:89] op_sel_hi:[1,0,1]
	s_nop 0
	v_pk_fma_f32 v[88:89], v[84:85], v[84:85], v[90:91]
	v_lshlrev_b32_e32 v90, 16, v137
	v_and_b32_e32 v91, 0xffff0000, v137
	v_pk_fma_f32 v[86:87], v[86:87], 0.5, v[90:91] op_sel_hi:[1,0,1]
	v_lshlrev_b32_e32 v90, 16, v138
	v_and_b32_e32 v91, 0xffff0000, v138
	v_pk_fma_f32 v[88:89], v[86:87], v[86:87], v[88:89]
	v_pk_fma_f32 v[90:91], v[80:81], 0.5, v[90:91] op_sel_hi:[1,0,1]
	s_nop 0
	v_pk_fma_f32 v[80:81], v[90:91], v[90:91], v[88:89]
	v_lshlrev_b32_e32 v88, 16, v139
	v_and_b32_e32 v89, 0xffff0000, v139
	v_pk_fma_f32 v[88:89], v[82:83], 0.5, v[88:89] op_sel_hi:[1,0,1]
	s_nop 0
	v_pk_fma_f32 v[80:81], v[88:89], v[88:89], v[80:81]
	s_nop 0
	v_add_f32_e32 v83, v80, v81
	ds_bpermute_b32 v98, v192, v83
	v_lshl_add_u64 v[80:81], s[16:17], 0, v[180:181]
	v_lshl_add_u64 v[96:97], v[172:173], 1, v[80:81]
	global_store_dwordx4 v[96:97], v[92:95], off sc1
	v_cvt_pk_bf16_f32 v82, v84, v85
	s_waitcnt lgkmcnt(0)
	v_add_f32_e32 v80, v83, v98
	ds_bpermute_b32 v81, v112, v80
	v_cvt_pk_bf16_f32 v83, v86, v87
	v_cvt_pk_bf16_f32 v84, v90, v91
	v_cvt_pk_bf16_f32 v85, v88, v89
	global_store_dwordx4 v[96:97], v[82:85], off offset:256 sc1
	s_and_saveexec_b64 s[48:49], s[4:5]
	s_cbranch_execz .LBB0_1190
	s_waitcnt lgkmcnt(0)
	v_add_f32_e32 v80, v80, v81
	ds_write_b32 v187, v80 offset:512
.LBB0_1190:
	s_or_b64 exec, exec, s[48:49]
	v_lshlrev_b32_e32 v82, 16, v133
	v_and_b32_e32 v83, 0xffff0000, v133
	v_lshlrev_b32_e32 v80, 16, v132
	s_waitcnt lgkmcnt(0)
	v_and_b32_e32 v81, 0xffff0000, v132
	v_pk_fma_f32 v[78:79], v[78:79], 0.5, v[82:83] op_sel_hi:[1,0,1]
	v_pk_fma_f32 v[80:81], v[76:77], 0.5, v[80:81] op_sel_hi:[1,0,1]
	v_pk_mul_f32 v[82:83], v[78:79], v[78:79]
	v_cvt_pk_bf16_f32 v76, v80, v81
	v_cvt_pk_bf16_f32 v77, v78, v79
	v_lshlrev_b32_e32 v78, 16, v134
	v_and_b32_e32 v79, 0xffff0000, v134
	v_pk_fma_f32 v[80:81], v[80:81], v[80:81], v[82:83]
	v_pk_fma_f32 v[72:73], v[72:73], 0.5, v[78:79] op_sel_hi:[1,0,1]
	s_nop 0
	v_pk_fma_f32 v[80:81], v[72:73], v[72:73], v[80:81]
	v_cvt_pk_bf16_f32 v78, v72, v73
	v_lshlrev_b32_e32 v72, 16, v135
	v_and_b32_e32 v73, 0xffff0000, v135
	v_pk_fma_f32 v[72:73], v[74:75], 0.5, v[72:73] op_sel_hi:[1,0,1]
	s_nop 0
	v_pk_fma_f32 v[74:75], v[72:73], v[72:73], v[80:81]
	v_cvt_pk_bf16_f32 v79, v72, v73
	v_lshlrev_b32_e32 v72, 16, v128
	v_and_b32_e32 v73, 0xffff0000, v128
	v_pk_fma_f32 v[68:69], v[68:69], 0.5, v[72:73] op_sel_hi:[1,0,1]
	s_nop 0
	v_pk_fma_f32 v[72:73], v[68:69], v[68:69], v[74:75]
	v_lshlrev_b32_e32 v74, 16, v129
	v_and_b32_e32 v75, 0xffff0000, v129
	v_pk_fma_f32 v[70:71], v[70:71], 0.5, v[74:75] op_sel_hi:[1,0,1]
	v_lshlrev_b32_e32 v74, 16, v130
	v_and_b32_e32 v75, 0xffff0000, v130
	v_pk_fma_f32 v[72:73], v[70:71], v[70:71], v[72:73]
	v_pk_fma_f32 v[74:75], v[64:65], 0.5, v[74:75] op_sel_hi:[1,0,1]
	s_nop 0
	v_pk_fma_f32 v[64:65], v[74:75], v[74:75], v[72:73]
	v_lshlrev_b32_e32 v72, 16, v131
	v_and_b32_e32 v73, 0xffff0000, v131
	v_pk_fma_f32 v[72:73], v[66:67], 0.5, v[72:73] op_sel_hi:[1,0,1]
	s_nop 0
	v_pk_fma_f32 v[64:65], v[72:73], v[72:73], v[64:65]
	s_nop 0
	v_add_f32_e32 v67, v64, v65
	ds_bpermute_b32 v82, v192, v67
	v_lshl_add_u64 v[64:65], s[16:17], 0, v[178:179]
	v_lshl_add_u64 v[80:81], v[172:173], 1, v[64:65]
	global_store_dwordx4 v[80:81], v[76:79], off sc1
	v_cvt_pk_bf16_f32 v66, v68, v69
	s_waitcnt lgkmcnt(0)
	v_add_f32_e32 v64, v67, v82
	ds_bpermute_b32 v65, v112, v64
	v_cvt_pk_bf16_f32 v67, v70, v71
	v_cvt_pk_bf16_f32 v68, v74, v75
	v_cvt_pk_bf16_f32 v69, v72, v73
	global_store_dwordx4 v[80:81], v[66:69], off offset:256 sc1
	s_and_saveexec_b64 s[48:49], s[4:5]
	s_cbranch_execz .LBB0_1192
	s_waitcnt lgkmcnt(0)
	v_add_f32_e32 v64, v64, v65
	ds_write_b32 v187, v64 offset:768
.LBB0_1192:
	s_or_b64 exec, exec, s[48:49]
	s_waitcnt lgkmcnt(0)
	v_lshlrev_b64 v[64:65], 11, v[176:177]
	v_lshl_add_u64 v[102:103], v[64:65], 0, s[26:27]
	v_lshl_add_u64 v[66:67], v[174:175], 0, v[102:103]
	global_load_dwordx4 v[94:97], v[66:67], off
	global_load_dwordx4 v[98:101], v[66:67], off offset:256
	v_lshl_add_u64 v[92:93], v[64:65], 0, s[28:29]
	v_lshl_add_u64 v[90:91], v[64:65], 0, s[30:31]
	v_lshl_add_u64 v[88:89], v[64:65], 0, s[44:45]
	v_lshl_add_u64 v[64:65], v[174:175], 0, v[92:93]
	v_lshl_add_u64 v[66:67], v[174:175], 0, v[90:91]
	v_lshl_add_u64 v[104:105], v[174:175], 0, v[88:89]
	global_load_dwordx4 v[84:87], v[64:65], off
	global_load_dwordx4 v[80:83], v[64:65], off offset:256
	global_load_dwordx4 v[76:79], v[66:67], off
	global_load_dwordx4 v[72:75], v[66:67], off offset:256
	global_load_dwordx4 v[68:71], v[104:105], off
	s_nop 0
	global_load_dwordx4 v[64:67], v[104:105], off offset:256
	s_waitcnt vmcnt(7)
	v_lshlrev_b32_e32 v104, 16, v94
	v_and_b32_e32 v105, 0xffff0000, v94
	v_lshlrev_b32_e32 v94, 16, v95
	v_and_b32_e32 v95, 0xffff0000, v95
	v_lshlrev_b32_e32 v106, 16, v96
	v_and_b32_e32 v107, 0xffff0000, v96
	v_lshlrev_b32_e32 v96, 16, v97
	v_and_b32_e32 v97, 0xffff0000, v97
	s_waitcnt vmcnt(6)
	v_lshlrev_b32_e32 v108, 16, v98
	v_and_b32_e32 v109, 0xffff0000, v98
	v_lshlrev_b32_e32 v98, 16, v99
	v_and_b32_e32 v99, 0xffff0000, v99
	v_lshlrev_b32_e32 v110, 16, v100
	v_and_b32_e32 v111, 0xffff0000, v100
	v_pk_fma_f32 v[62:63], v[62:63], 0.5, v[94:95] op_sel_hi:[1,0,1]
	v_pk_fma_f32 v[60:61], v[60:61], 0.5, v[104:105] op_sel_hi:[1,0,1]
	v_pk_fma_f32 v[58:59], v[58:59], 0.5, v[96:97] op_sel_hi:[1,0,1]
	v_pk_fma_f32 v[96:97], v[54:55], 0.5, v[98:99] op_sel_hi:[1,0,1]
	v_pk_fma_f32 v[98:99], v[48:49], 0.5, v[110:111] op_sel_hi:[1,0,1]
	v_pk_mul_f32 v[48:49], v[62:63], v[62:63]
	v_pk_fma_f32 v[56:57], v[56:57], 0.5, v[106:107] op_sel_hi:[1,0,1]
	v_pk_fma_f32 v[48:49], v[60:61], v[60:61], v[48:49]
	v_pk_fma_f32 v[94:95], v[52:53], 0.5, v[108:109] op_sel_hi:[1,0,1]
	v_pk_fma_f32 v[48:49], v[56:57], v[56:57], v[48:49]
	v_lshlrev_b32_e32 v100, 16, v101
	v_pk_fma_f32 v[48:49], v[58:59], v[58:59], v[48:49]
	v_and_b32_e32 v101, 0xffff0000, v101
	v_pk_fma_f32 v[48:49], v[94:95], v[94:95], v[48:49]
	v_cvt_pk_bf16_f32 v52, v60, v61
	v_cvt_pk_bf16_f32 v53, v62, v63
	v_cvt_pk_bf16_f32 v54, v56, v57
	v_pk_fma_f32 v[56:57], v[50:51], 0.5, v[100:101] op_sel_hi:[1,0,1]
	v_pk_fma_f32 v[48:49], v[96:97], v[96:97], v[48:49]
	v_cvt_pk_bf16_f32 v55, v58, v59
	s_nop 0
	v_pk_fma_f32 v[48:49], v[98:99], v[98:99], v[48:49]
	s_nop 0
	v_pk_fma_f32 v[48:49], v[56:57], v[56:57], v[48:49]
	s_nop 0
	v_add_f32_e32 v51, v48, v49
	ds_bpermute_b32 v60, v192, v51
	v_lshl_add_u64 v[48:49], s[16:17], 0, v[102:103]
	v_lshl_add_u64 v[58:59], v[172:173], 1, v[48:49]
	global_store_dwordx4 v[58:59], v[52:55], off sc1
	v_cvt_pk_bf16_f32 v50, v94, v95
	s_waitcnt lgkmcnt(0)
	v_add_f32_e32 v48, v51, v60
	ds_bpermute_b32 v49, v112, v48
	v_cvt_pk_bf16_f32 v51, v96, v97
	v_cvt_pk_bf16_f32 v52, v98, v99
	v_cvt_pk_bf16_f32 v53, v56, v57
	global_store_dwordx4 v[58:59], v[50:53], off offset:256 sc1
	s_and_saveexec_b64 s[48:49], s[4:5]
	s_cbranch_execz .LBB0_1194
	s_waitcnt lgkmcnt(0)
	v_add_f32_e32 v48, v48, v49
	ds_write_b32 v187, v48 offset:2048
.LBB0_1194:
	s_or_b64 exec, exec, s[48:49]
	s_waitcnt vmcnt(7)
	v_lshlrev_b32_e32 v50, 16, v85
	v_and_b32_e32 v51, 0xffff0000, v85
	v_lshlrev_b32_e32 v48, 16, v84
	s_waitcnt lgkmcnt(0)
	v_and_b32_e32 v49, 0xffff0000, v84
	v_pk_fma_f32 v[46:47], v[46:47], 0.5, v[50:51] op_sel_hi:[1,0,1]
	v_pk_fma_f32 v[48:49], v[44:45], 0.5, v[48:49] op_sel_hi:[1,0,1]
	v_pk_mul_f32 v[50:51], v[46:47], v[46:47]
	v_cvt_pk_bf16_f32 v44, v48, v49
	v_cvt_pk_bf16_f32 v45, v46, v47
	v_lshlrev_b32_e32 v46, 16, v86
	v_and_b32_e32 v47, 0xffff0000, v86
	v_pk_fma_f32 v[48:49], v[48:49], v[48:49], v[50:51]
	v_pk_fma_f32 v[40:41], v[40:41], 0.5, v[46:47] op_sel_hi:[1,0,1]
	s_nop 0
	v_pk_fma_f32 v[48:49], v[40:41], v[40:41], v[48:49]
	v_cvt_pk_bf16_f32 v46, v40, v41
	v_lshlrev_b32_e32 v40, 16, v87
	v_and_b32_e32 v41, 0xffff0000, v87
	v_pk_fma_f32 v[40:41], v[42:43], 0.5, v[40:41] op_sel_hi:[1,0,1]
	s_nop 0
	v_pk_fma_f32 v[42:43], v[40:41], v[40:41], v[48:49]
	v_cvt_pk_bf16_f32 v47, v40, v41
	s_waitcnt vmcnt(6)
	v_lshlrev_b32_e32 v40, 16, v80
	v_and_b32_e32 v41, 0xffff0000, v80
	v_pk_fma_f32 v[36:37], v[36:37], 0.5, v[40:41] op_sel_hi:[1,0,1]
	s_nop 0
	v_pk_fma_f32 v[40:41], v[36:37], v[36:37], v[42:43]
	v_lshlrev_b32_e32 v42, 16, v81
	v_and_b32_e32 v43, 0xffff0000, v81
	v_pk_fma_f32 v[38:39], v[38:39], 0.5, v[42:43] op_sel_hi:[1,0,1]
	v_lshlrev_b32_e32 v42, 16, v82
	v_and_b32_e32 v43, 0xffff0000, v82
	v_pk_fma_f32 v[40:41], v[38:39], v[38:39], v[40:41]
	v_pk_fma_f32 v[42:43], v[32:33], 0.5, v[42:43] op_sel_hi:[1,0,1]
	s_nop 0
	v_pk_fma_f32 v[32:33], v[42:43], v[42:43], v[40:41]
	v_lshlrev_b32_e32 v40, 16, v83
	v_and_b32_e32 v41, 0xffff0000, v83
	v_pk_fma_f32 v[40:41], v[34:35], 0.5, v[40:41] op_sel_hi:[1,0,1]
	s_nop 0
	v_pk_fma_f32 v[32:33], v[40:41], v[40:41], v[32:33]
	s_nop 0
	v_add_f32_e32 v35, v32, v33
	ds_bpermute_b32 v50, v192, v35
	v_lshl_add_u64 v[32:33], s[16:17], 0, v[92:93]
	v_lshl_add_u64 v[48:49], v[172:173], 1, v[32:33]
	global_store_dwordx4 v[48:49], v[44:47], off sc1
	v_cvt_pk_bf16_f32 v34, v36, v37
	s_waitcnt lgkmcnt(0)
	v_add_f32_e32 v32, v35, v50
	ds_bpermute_b32 v33, v112, v32
	v_cvt_pk_bf16_f32 v35, v38, v39
	v_cvt_pk_bf16_f32 v36, v42, v43
	v_cvt_pk_bf16_f32 v37, v40, v41
	global_store_dwordx4 v[48:49], v[34:37], off offset:256 sc1
	s_and_saveexec_b64 s[48:49], s[4:5]
	s_cbranch_execz .LBB0_1196
	s_waitcnt lgkmcnt(0)
	v_add_f32_e32 v32, v32, v33
	ds_write_b32 v187, v32 offset:2304
.LBB0_1196:
	s_or_b64 exec, exec, s[48:49]
	s_waitcnt vmcnt(7)
	v_lshlrev_b32_e32 v34, 16, v77
	v_and_b32_e32 v35, 0xffff0000, v77
	v_lshlrev_b32_e32 v32, 16, v76
	s_waitcnt lgkmcnt(0)
	v_and_b32_e32 v33, 0xffff0000, v76
	v_pk_fma_f32 v[30:31], v[30:31], 0.5, v[34:35] op_sel_hi:[1,0,1]
	v_pk_fma_f32 v[32:33], v[28:29], 0.5, v[32:33] op_sel_hi:[1,0,1]
	v_pk_mul_f32 v[34:35], v[30:31], v[30:31]
	v_cvt_pk_bf16_f32 v28, v32, v33
	v_cvt_pk_bf16_f32 v29, v30, v31
	v_lshlrev_b32_e32 v30, 16, v78
	v_and_b32_e32 v31, 0xffff0000, v78
	v_pk_fma_f32 v[32:33], v[32:33], v[32:33], v[34:35]
	v_pk_fma_f32 v[24:25], v[24:25], 0.5, v[30:31] op_sel_hi:[1,0,1]
	s_nop 0
	v_pk_fma_f32 v[32:33], v[24:25], v[24:25], v[32:33]
	v_cvt_pk_bf16_f32 v30, v24, v25
	v_lshlrev_b32_e32 v24, 16, v79
	v_and_b32_e32 v25, 0xffff0000, v79
	v_pk_fma_f32 v[24:25], v[26:27], 0.5, v[24:25] op_sel_hi:[1,0,1]
	s_nop 0
	v_pk_fma_f32 v[26:27], v[24:25], v[24:25], v[32:33]
	v_cvt_pk_bf16_f32 v31, v24, v25
	s_waitcnt vmcnt(6)
	v_lshlrev_b32_e32 v24, 16, v72
	v_and_b32_e32 v25, 0xffff0000, v72
	v_pk_fma_f32 v[20:21], v[20:21], 0.5, v[24:25] op_sel_hi:[1,0,1]
	s_nop 0
	v_pk_fma_f32 v[24:25], v[20:21], v[20:21], v[26:27]
	v_lshlrev_b32_e32 v26, 16, v73
	v_and_b32_e32 v27, 0xffff0000, v73
	v_pk_fma_f32 v[22:23], v[22:23], 0.5, v[26:27] op_sel_hi:[1,0,1]
	v_lshlrev_b32_e32 v26, 16, v74
	v_and_b32_e32 v27, 0xffff0000, v74
	v_pk_fma_f32 v[24:25], v[22:23], v[22:23], v[24:25]
	v_pk_fma_f32 v[26:27], v[16:17], 0.5, v[26:27] op_sel_hi:[1,0,1]
	s_nop 0
	v_pk_fma_f32 v[16:17], v[26:27], v[26:27], v[24:25]
	v_lshlrev_b32_e32 v24, 16, v75
	v_and_b32_e32 v25, 0xffff0000, v75
	v_pk_fma_f32 v[24:25], v[18:19], 0.5, v[24:25] op_sel_hi:[1,0,1]
	s_nop 0
	v_pk_fma_f32 v[16:17], v[24:25], v[24:25], v[16:17]
	s_nop 0
	v_add_f32_e32 v19, v16, v17
	ds_bpermute_b32 v34, v192, v19
	v_lshl_add_u64 v[16:17], s[16:17], 0, v[90:91]
	v_lshl_add_u64 v[32:33], v[172:173], 1, v[16:17]
	global_store_dwordx4 v[32:33], v[28:31], off sc1
	v_cvt_pk_bf16_f32 v18, v20, v21
	s_waitcnt lgkmcnt(0)
	v_add_f32_e32 v16, v19, v34
	ds_bpermute_b32 v17, v112, v16
	v_cvt_pk_bf16_f32 v19, v22, v23
	v_cvt_pk_bf16_f32 v20, v26, v27
	v_cvt_pk_bf16_f32 v21, v24, v25
	global_store_dwordx4 v[32:33], v[18:21], off offset:256 sc1
	s_and_saveexec_b64 s[48:49], s[4:5]
	s_cbranch_execz .LBB0_1198
	s_waitcnt lgkmcnt(0)
	v_add_f32_e32 v16, v16, v17
	ds_write_b32 v187, v16 offset:2560
.LBB0_1198:
	s_or_b64 exec, exec, s[48:49]
	s_waitcnt vmcnt(7)
	v_lshlrev_b32_e32 v18, 16, v69
	v_and_b32_e32 v19, 0xffff0000, v69
	v_lshlrev_b32_e32 v16, 16, v68
	s_waitcnt lgkmcnt(0)
	v_and_b32_e32 v17, 0xffff0000, v68
	v_pk_fma_f32 v[14:15], v[14:15], 0.5, v[18:19] op_sel_hi:[1,0,1]
	v_pk_fma_f32 v[16:17], v[12:13], 0.5, v[16:17] op_sel_hi:[1,0,1]
	v_pk_mul_f32 v[18:19], v[14:15], v[14:15]
	v_cvt_pk_bf16_f32 v12, v16, v17
	v_cvt_pk_bf16_f32 v13, v14, v15
	v_lshlrev_b32_e32 v14, 16, v70
	v_and_b32_e32 v15, 0xffff0000, v70
	v_pk_fma_f32 v[16:17], v[16:17], v[16:17], v[18:19]
	v_pk_fma_f32 v[8:9], v[8:9], 0.5, v[14:15] op_sel_hi:[1,0,1]
	s_nop 0
	v_pk_fma_f32 v[16:17], v[8:9], v[8:9], v[16:17]
	v_cvt_pk_bf16_f32 v14, v8, v9
	v_lshlrev_b32_e32 v8, 16, v71
	v_and_b32_e32 v9, 0xffff0000, v71
	v_pk_fma_f32 v[8:9], v[10:11], 0.5, v[8:9] op_sel_hi:[1,0,1]
	s_nop 0
	v_pk_fma_f32 v[10:11], v[8:9], v[8:9], v[16:17]
	v_cvt_pk_bf16_f32 v15, v8, v9
	s_waitcnt vmcnt(6)
	v_lshlrev_b32_e32 v8, 16, v64
	v_and_b32_e32 v9, 0xffff0000, v64
	v_pk_fma_f32 v[4:5], v[4:5], 0.5, v[8:9] op_sel_hi:[1,0,1]
	s_nop 0
	v_pk_fma_f32 v[8:9], v[4:5], v[4:5], v[10:11]
	v_lshlrev_b32_e32 v10, 16, v65
	v_and_b32_e32 v11, 0xffff0000, v65
	v_pk_fma_f32 v[6:7], v[6:7], 0.5, v[10:11] op_sel_hi:[1,0,1]
	v_lshlrev_b32_e32 v10, 16, v66
	v_and_b32_e32 v11, 0xffff0000, v66
	v_pk_fma_f32 v[8:9], v[6:7], v[6:7], v[8:9]
	v_pk_fma_f32 v[10:11], v[0:1], 0.5, v[10:11] op_sel_hi:[1,0,1]
	s_nop 0
	v_pk_fma_f32 v[0:1], v[10:11], v[10:11], v[8:9]
	v_lshlrev_b32_e32 v8, 16, v67
	v_and_b32_e32 v9, 0xffff0000, v67
	v_pk_fma_f32 v[8:9], v[2:3], 0.5, v[8:9] op_sel_hi:[1,0,1]
	s_nop 0
	v_pk_fma_f32 v[0:1], v[8:9], v[8:9], v[0:1]
	s_nop 0
	v_add_f32_e32 v3, v0, v1
	ds_bpermute_b32 v18, v192, v3
	v_lshl_add_u64 v[0:1], s[16:17], 0, v[88:89]
	v_lshl_add_u64 v[16:17], v[172:173], 1, v[0:1]
	global_store_dwordx4 v[16:17], v[12:15], off sc1
	v_cvt_pk_bf16_f32 v2, v4, v5
	s_waitcnt lgkmcnt(0)
	v_add_f32_e32 v0, v3, v18
	ds_bpermute_b32 v1, v112, v0
	v_cvt_pk_bf16_f32 v3, v6, v7
	v_cvt_pk_bf16_f32 v4, v10, v11
	v_cvt_pk_bf16_f32 v5, v8, v9
	global_store_dwordx4 v[16:17], v[2:5], off offset:256 sc1
	s_and_saveexec_b64 s[48:49], s[4:5]
	s_cbranch_execz .LBB0_1200
	s_waitcnt lgkmcnt(0)
	v_add_f32_e32 v0, v0, v1
	ds_write_b32 v187, v0 offset:2816
.LBB0_1200:
	s_or_b64 exec, exec, s[48:49]
	s_waitcnt lgkmcnt(0)
	s_barrier
	s_and_saveexec_b64 s[48:49], s[6:7]
	s_cbranch_execz .LBB0_1202
	s_waitcnt lgkmcnt(0)
	ds_read_b128 v[0:3], v191
	v_or_b32_e32 v4, s13, v157
	v_ashrrev_i32_e32 v5, 31, v4
	s_ashr_i32 s13, s12, 31
	s_waitcnt lgkmcnt(0)
	v_mov_b32_e32 v6, v1
	v_mov_b32_e32 v7, v2
	v_mov_b32_e32 v1, v3
	v_pk_add_f32 v[0:1], v[6:7], v[0:1]
	s_nop 0
	v_add_f32_e32 v2, v0, v1
	v_lshl_add_u64 v[0:1], v[4:5], 4, s[20:21]
	v_lshl_add_u64 v[0:1], s[12:13], 2, v[0:1]
	global_store_dword v[0:1], v2, off sc1
